# attention: fixed softmax shift from the first 64 keys (no per-sub-tile row max / rescale vote), end-of-unit overflow+NaN screen with workgroup vote and exact running-max rerun as fallback
# speedup vs baseline: 1.0220x; 1.0220x over previous
; #define LAS __attribute__((address_space(3)))
; __device__ __forceinline__ int opaque_tid() { int t = threadIdx.x; asm volatile("" : "+v"(t)); return t; }
; __device__ __forceinline__ int v_st_nat(int k, int c) { return ((k >> 3) * 2 + (c >> 5)) * 512 + ((k & 7) * 32 + (c & 31)) * 2; }
; __device__ __forceinline__ int v_rd_base(int lane) { return ((lane & 3) << 3) | (((lane >> 2) & 3) << 6) | (((lane >> 4) & 1) << 5) | (((lane >> 5) & 1) << 8); }
; #define AT_LOAD(K0, K1, V0, V1, T) do { const size_t e_ = (size_t)(128 * (T) + sr) * 64 + sc; \
;         K0 = *(const bf16x8*)(kcp + e_); V0 = *(const bf16x8*)(vcp + e_); K1 = *(const bf16x8*)(kcp + e_ + 64 * 64); V1 = *(const bf16x8*)(vcp + e_ + 64 * 64); } while (0)
; #define AT_STORE(K0, K1, V0, V1, BUF) do { *(LAS bf16x8*)(lds + AT_K + (BUF) * AT_KB + kst0) = K0; *(LAS bf16x8*)(lds + AT_K + (BUF) * AT_KB + kst1) = K1; \
;         *(LAS bf16x8*)(lds + AT_V + (BUF) * AT_VB + vst0) = V0; *(LAS bf16x8*)(lds + AT_V + (BUF) * AT_VB + vst1) = V1; } while (0)
; template <int VAR>
; __device__ __forceinline__ void attn_unit(const Args& a, int l, int b, int h, int qrow0  , bool ctxu, const bf16* Z, bf16* Y, LAS unsigned char* lds) {
;     const int tid = opaque_tid(), lane = tid & 63, wave = __builtin_amdgcn_readfirstlane(tid >> 6), r32 = lane & 31, hi = lane >> 5;
;     const int comp = wave >> 2, wq = wave & 3;
;     const int NT = ctxu ? 2 : 66;
;     const bf16* kcp = (const bf16*)(a.ws + WS_KC) + (size_t)(b * 4 + h) * 8448 * 64; const bf16* vcp = (const bf16*)(a.ws + WS_VC) + (size_t)(b * 4 + h) * 8448 * 64;
;     bf16x8 q0, q1;
;     { const bf16* qp = Z + (size_t)(qrow0 + wq * 32 + r32) * DIN + 512 + h * 64 + comp * 32 + hi * 8; q0 = *(const bf16x8*)(qp); q1 = *(const bf16x8*)(qp + 16); }
;     const int sr = tid >> 3, sc = (tid & 7) * 8;
;     const int kst0 = sr * 144 + sc * 2, kst1 = kst0 + 64 * 144, vst0 = v_st_nat(sr, sc), vst1 = v_st_nat(sr + 64, sc);
;     const int vb0 = (int)(unsigned)(uintptr_t)(lds + AT_V) + v_rd_base(lane);
;     LAS float* wsf = (LAS float*)(lds + AT_WS) + wave * 64;
;     f32x16 negm = f32x16{}, o0 = f32x16{}, o1 = f32x16{}, lacc = f32x16{};
;     float m = 0.f;
;     bf16x8 ka0, ka1, va0, va1, kb0, kb1, vb0_, vb1_;
;     ...
;     AT_LOAD(ka0, ka1, va0, va1, 0); AT_LOAD(kb0, kb1, vb0_, vb1_, 1); AT_STORE(ka0, ka1, va0, va1, 0);
.LBB0_431:
	v_mov_b32_e32 v79, 0
	v_readfirstlane_b32 s36, v230
	v_readfirstlane_b32 s37, v231
	s_mov_b32 s94, 1
	s_mov_b32 s95, 1
	s_mov_b32 s33, 0
	s_lshr_b32 s50, s29, 6
	s_lshl_b32 s51, s50, 10
	s_lshl_b32 s93, s50, 8
	s_lshl_b32 s50, s50, 3
	v_lshrrev_b32_e32 v132, 3, v227
	v_add_u32_e32 v132, s50, v132
	v_bfe_u32 v133, v132, 1, 3
	v_and_b32_e32 v134, 7, v227
	v_xor_b32_e32 v134, v134, v133
	v_lshlrev_b32_e32 v132, 7, v132
	v_lshl_or_b32 v158, v134, 4, v132
	v_add_u32_e32 v159, 0x2000, v158
	v_bfe_u32 v132, v227, 2, 3
	v_add_u32_e32 v132, s50, v132
	v_lshrrev_b32_e32 v133, 5, v227
	v_and_b32_e32 v134, 3, v227
	v_lshlrev_b32_e32 v133, 6, v133
	v_lshl_or_b32 v133, v134, 4, v133
	v_lshl_or_b32 v160, v132, 7, v133
	v_add_u32_e32 v161, 0x2000, v160
	s_lshl_b32 s50, s8, 2
	v_add_u32_e32 v132, s50, v248
	v_bfe_u32 v133, v247, 1, 3
	v_xor_b32_e32 v132, v132, v133
	v_lshlrev_b32_e32 v133, 7, v247
	v_lshl_or_b32 v144, v132, 4, v133
	v_xor_b32_e32 v145, 32, v144
	v_add_u32_e32 v146, 0x3000, v249
	s_add_u32 s93, s93, 0x19800
	v_lshlrev_b32_e32 v132, 2, v247
	v_add_u32_e32 v148, s93, v132
	v_lshlrev_b32_e32 v132, 4, v248
	v_add_u32_e32 v147, s93, v132
	v_mov_b32_e32 v132, 0x19880
	v_mov_b32_e32 v133, 0
	ds_write_b32 v132, v133
	v_mov_b32_e32 v80, 0
	v_mov_b32_e32 v200, 0
	v_mov_b32_e32 v81, 0
	v_mov_b32_e32 v201, 0
	v_mov_b32_e32 v82, 0
	v_mov_b32_e32 v202, 0
	v_mov_b32_e32 v83, 0
	v_mov_b32_e32 v203, 0
	v_mov_b32_e32 v84, 0
	v_mov_b32_e32 v204, 0
	v_mov_b32_e32 v85, 0
	v_mov_b32_e32 v205, 0
	v_mov_b32_e32 v86, 0
	v_mov_b32_e32 v206, 0
	v_mov_b32_e32 v87, 0
	v_mov_b32_e32 v207, 0
	v_mov_b32_e32 v88, 0
	v_mov_b32_e32 v208, 0
	v_mov_b32_e32 v89, 0
	v_mov_b32_e32 v209, 0
	v_mov_b32_e32 v90, 0
	v_mov_b32_e32 v210, 0
	v_mov_b32_e32 v91, 0
	v_mov_b32_e32 v211, 0
	v_mov_b32_e32 v92, 0
	v_mov_b32_e32 v212, 0
	v_mov_b32_e32 v93, 0
	v_mov_b32_e32 v213, 0
	v_mov_b32_e32 v94, 0
	v_mov_b32_e32 v214, 0
	v_mov_b32_e32 v95, 0
	v_mov_b32_e32 v215, 0
	v_mov_b32_e32 v128, 0
	v_mov_b32_e32 v129, 0
	v_mov_b32_e32 v130, 0
	v_mov_b32_e32 v131, 0
	v_mov_b32_e32 v149, 0
	s_sub_u32 s36, s36, s51
	s_subb_u32 s37, s37, 0
	s_add_u32 s48, s36, 0x1d200000
	s_addc_u32 s49, s37, 0
	s_add_u32 s36, s36, 0x1c000000
	s_addc_u32 s37, s37, 0
	s_cmp_eq_u32 s8, 0
	s_cbranch_scc0 .Lat_noprioF
	s_setprio 1

.Lat_floop:
	s_waitcnt lgkmcnt(0)
	v_mfma_f32_32x32x16_bf16 v[96:111], v[48:51], v[136:139], v[32:47]
	ds_read_b64_tr_b16 v[168:169], v146 offset:0
	ds_read_b64_tr_b16 v[170:171], v146 offset:1024
	ds_read_b64_tr_b16 v[172:173], v146 offset:512
	ds_read_b64_tr_b16 v[174:175], v146 offset:1536
	v_mfma_f32_32x32x16_bf16 v[96:111], v[52:55], v[140:143], v[96:111]
	ds_read_b64_tr_b16 v[176:177], v146 offset:2048
	ds_read_b64_tr_b16 v[178:179], v146 offset:3072
	ds_read_b64_tr_b16 v[180:181], v146 offset:2560
	ds_read_b64_tr_b16 v[182:183], v146 offset:3584
	v_mfma_f32_32x32x16_bf16 v[112:127], v[56:59], v[136:139], v[32:47]
	ds_read_b64_tr_b16 v[184:185], v146 offset:4096
	ds_read_b64_tr_b16 v[186:187], v146 offset:5120
	ds_read_b64_tr_b16 v[188:189], v146 offset:4608
	ds_read_b64_tr_b16 v[190:191], v146 offset:5632
	v_mfma_f32_32x32x16_bf16 v[112:127], v[60:63], v[140:143], v[112:127]
	ds_read_b64_tr_b16 v[192:193], v146 offset:6144
	ds_read_b64_tr_b16 v[194:195], v146 offset:7168
	ds_read_b64_tr_b16 v[196:197], v146 offset:6656
	ds_read_b64_tr_b16 v[198:199], v146 offset:7680
	s_cmp_lg_u32 s94, 0
	s_cbranch_scc1 .Lat_ffirsta
.Lat_fbacka:
	v_exp_f32_e32 v96, v96
	v_exp_f32_e32 v97, v97
	v_exp_f32_e32 v98, v98
	v_exp_f32_e32 v99, v99
	v_exp_f32_e32 v100, v100
	v_exp_f32_e32 v101, v101
	v_exp_f32_e32 v102, v102
	v_exp_f32_e32 v103, v103
	v_cvt_pk_bf16_f32 v162, v96, v97
	v_cvt_pk_bf16_f32 v163, v98, v99
	v_cvt_pk_bf16_f32 v164, v100, v101
	v_cvt_pk_bf16_f32 v165, v102, v103
	v_pk_add_f32 v[128:129], v[128:129], v[96:97]
	v_pk_add_f32 v[128:129], v[128:129], v[98:99]
	v_pk_add_f32 v[128:129], v[128:129], v[100:101]
	v_pk_add_f32 v[128:129], v[128:129], v[102:103]
	s_waitcnt lgkmcnt(12)
	v_mfma_f32_32x32x16_bf16 v[0:15], v[162:165], v[168:171], v[0:15]
	v_exp_f32_e32 v104, v104
	v_exp_f32_e32 v105, v105
	v_exp_f32_e32 v106, v106
	v_exp_f32_e32 v107, v107
	v_mfma_f32_32x32x16_bf16 v[16:31], v[162:165], v[172:175], v[16:31]
	v_exp_f32_e32 v108, v108
	v_exp_f32_e32 v109, v109
	v_exp_f32_e32 v110, v110
	v_exp_f32_e32 v111, v111
	v_cvt_pk_bf16_f32 v162, v104, v105
	v_cvt_pk_bf16_f32 v163, v106, v107
	v_cvt_pk_bf16_f32 v164, v108, v109
	v_cvt_pk_bf16_f32 v165, v110, v111
	v_pk_add_f32 v[128:129], v[128:129], v[104:105]
	v_pk_add_f32 v[128:129], v[128:129], v[106:107]
	v_pk_add_f32 v[128:129], v[128:129], v[108:109]
	v_pk_add_f32 v[128:129], v[128:129], v[110:111]
	s_waitcnt lgkmcnt(8)
	v_mfma_f32_32x32x16_bf16 v[0:15], v[162:165], v[176:179], v[0:15]
	v_exp_f32_e32 v112, v112
	v_exp_f32_e32 v113, v113
	v_exp_f32_e32 v114, v114
	v_exp_f32_e32 v115, v115
	v_mfma_f32_32x32x16_bf16 v[16:31], v[162:165], v[180:183], v[16:31]
	v_mfma_f32_32x32x16_bf16 v[96:111], v[48:51], v[150:153], v[64:79]
	v_exp_f32_e32 v116, v116
	v_exp_f32_e32 v117, v117
	v_exp_f32_e32 v118, v118
	v_exp_f32_e32 v119, v119
	v_mfma_f32_32x32x16_bf16 v[96:111], v[52:55], v[154:157], v[96:111]
	v_cvt_pk_bf16_f32 v162, v112, v113
	v_cvt_pk_bf16_f32 v163, v114, v115
	v_cvt_pk_bf16_f32 v164, v116, v117
	v_cvt_pk_bf16_f32 v165, v118, v119
	v_pk_add_f32 v[128:129], v[128:129], v[112:113]
	v_pk_add_f32 v[128:129], v[128:129], v[114:115]
	v_pk_add_f32 v[128:129], v[128:129], v[116:117]
	v_pk_add_f32 v[128:129], v[128:129], v[118:119]
	s_waitcnt lgkmcnt(4)
	v_mfma_f32_32x32x16_bf16 v[0:15], v[162:165], v[184:187], v[0:15]
	v_exp_f32_e32 v120, v120
	v_exp_f32_e32 v121, v121
	v_exp_f32_e32 v122, v122
	v_exp_f32_e32 v123, v123
	v_mfma_f32_32x32x16_bf16 v[16:31], v[162:165], v[188:191], v[16:31]
	v_exp_f32_e32 v124, v124
	v_exp_f32_e32 v125, v125
	v_exp_f32_e32 v126, v126
	v_exp_f32_e32 v127, v127
	v_cvt_pk_bf16_f32 v162, v120, v121
	v_cvt_pk_bf16_f32 v163, v122, v123
	v_cvt_pk_bf16_f32 v164, v124, v125
	v_cvt_pk_bf16_f32 v165, v126, v127
	v_pk_add_f32 v[128:129], v[128:129], v[120:121]
	v_pk_add_f32 v[128:129], v[128:129], v[122:123]
	v_pk_add_f32 v[128:129], v[128:129], v[124:125]
	v_pk_add_f32 v[128:129], v[128:129], v[126:127]
	v_mfma_f32_32x32x16_bf16 v[112:127], v[56:59], v[150:153], v[64:79]
	v_mfma_f32_32x32x16_bf16 v[112:127], v[60:63], v[154:157], v[112:127]
	s_waitcnt lgkmcnt(0)
	v_mfma_f32_32x32x16_bf16 v[0:15], v[162:165], v[192:195], v[0:15]
	v_mfma_f32_32x32x16_bf16 v[16:31], v[162:165], v[196:199], v[16:31]
	ds_read_b128 v[48:51], v144 offset:8192
	ds_read_b128 v[52:55], v145 offset:8192
	ds_read_b128 v[56:59], v144 offset:12288
	ds_read_b128 v[60:63], v145 offset:12288
	s_cmp_lg_u32 s95, 0
	s_cbranch_scc1 .Lat_ffirstb
.Lat_fbackb:
	v_exp_f32_e32 v96, v96
	v_exp_f32_e32 v97, v97
	v_exp_f32_e32 v98, v98
	v_exp_f32_e32 v99, v99
	v_exp_f32_e32 v100, v100
	v_exp_f32_e32 v101, v101
	v_exp_f32_e32 v102, v102
	v_exp_f32_e32 v103, v103
	v_cvt_pk_bf16_f32 v162, v96, v97
	v_cvt_pk_bf16_f32 v163, v98, v99
	v_cvt_pk_bf16_f32 v164, v100, v101
	v_cvt_pk_bf16_f32 v165, v102, v103
	v_pk_add_f32 v[130:131], v[130:131], v[96:97]
	v_pk_add_f32 v[130:131], v[130:131], v[98:99]
	v_pk_add_f32 v[130:131], v[130:131], v[100:101]
	v_pk_add_f32 v[130:131], v[130:131], v[102:103]
	v_mfma_f32_32x32x16_bf16 v[80:95], v[162:165], v[168:171], v[80:95]
	v_exp_f32_e32 v104, v104
	v_exp_f32_e32 v105, v105
	v_exp_f32_e32 v106, v106
	v_exp_f32_e32 v107, v107
	v_mfma_f32_32x32x16_bf16 v[200:215], v[162:165], v[172:175], v[200:215]
	v_exp_f32_e32 v108, v108
	v_exp_f32_e32 v109, v109
	v_exp_f32_e32 v110, v110
	v_exp_f32_e32 v111, v111
	v_cvt_pk_bf16_f32 v162, v104, v105
	v_cvt_pk_bf16_f32 v163, v106, v107
	v_cvt_pk_bf16_f32 v164, v108, v109
	v_cvt_pk_bf16_f32 v165, v110, v111
	v_pk_add_f32 v[130:131], v[130:131], v[104:105]
	v_pk_add_f32 v[130:131], v[130:131], v[106:107]
	v_pk_add_f32 v[130:131], v[130:131], v[108:109]
	v_pk_add_f32 v[130:131], v[130:131], v[110:111]
	v_mfma_f32_32x32x16_bf16 v[80:95], v[162:165], v[176:179], v[80:95]
	v_exp_f32_e32 v112, v112
	v_exp_f32_e32 v113, v113
	v_exp_f32_e32 v114, v114
	v_exp_f32_e32 v115, v115
	v_mfma_f32_32x32x16_bf16 v[200:215], v[162:165], v[180:183], v[200:215]
	v_exp_f32_e32 v116, v116
	v_exp_f32_e32 v117, v117
	v_exp_f32_e32 v118, v118
	v_exp_f32_e32 v119, v119
	v_cvt_pk_bf16_f32 v162, v112, v113
	v_cvt_pk_bf16_f32 v163, v114, v115
	v_cvt_pk_bf16_f32 v164, v116, v117
	v_cvt_pk_bf16_f32 v165, v118, v119
	v_pk_add_f32 v[130:131], v[130:131], v[112:113]
	v_pk_add_f32 v[130:131], v[130:131], v[114:115]
	v_pk_add_f32 v[130:131], v[130:131], v[116:117]
	v_pk_add_f32 v[130:131], v[130:131], v[118:119]
	v_mfma_f32_32x32x16_bf16 v[80:95], v[162:165], v[184:187], v[80:95]
	v_exp_f32_e32 v120, v120
	v_exp_f32_e32 v121, v121
	v_exp_f32_e32 v122, v122
	v_exp_f32_e32 v123, v123
	v_mfma_f32_32x32x16_bf16 v[200:215], v[162:165], v[188:191], v[200:215]
	v_exp_f32_e32 v124, v124
	v_exp_f32_e32 v125, v125
	v_exp_f32_e32 v126, v126
	v_exp_f32_e32 v127, v127
	v_cvt_pk_bf16_f32 v162, v120, v121
	v_cvt_pk_bf16_f32 v163, v122, v123
	v_cvt_pk_bf16_f32 v164, v124, v125
	v_cvt_pk_bf16_f32 v165, v126, v127
	v_pk_add_f32 v[130:131], v[130:131], v[120:121]
	v_pk_add_f32 v[130:131], v[130:131], v[122:123]
	v_pk_add_f32 v[130:131], v[130:131], v[124:125]
	v_pk_add_f32 v[130:131], v[130:131], v[126:127]
	v_mfma_f32_32x32x16_bf16 v[80:95], v[162:165], v[192:195], v[80:95]
	v_mfma_f32_32x32x16_bf16 v[200:215], v[162:165], v[196:199], v[200:215]
	s_waitcnt lgkmcnt(0)
	v_mfma_f32_32x32x16_bf16 v[96:111], v[48:51], v[136:139], v[32:47]
	ds_read_b64_tr_b16 v[168:169], v146 offset:8192
	ds_read_b64_tr_b16 v[170:171], v146 offset:9216
	ds_read_b64_tr_b16 v[172:173], v146 offset:8704
	ds_read_b64_tr_b16 v[174:175], v146 offset:9728
	v_mfma_f32_32x32x16_bf16 v[96:111], v[52:55], v[140:143], v[96:111]
	ds_read_b64_tr_b16 v[176:177], v146 offset:10240
	ds_read_b64_tr_b16 v[178:179], v146 offset:11264
	ds_read_b64_tr_b16 v[180:181], v146 offset:10752
	ds_read_b64_tr_b16 v[182:183], v146 offset:11776
	v_mfma_f32_32x32x16_bf16 v[112:127], v[56:59], v[136:139], v[32:47]
	ds_read_b64_tr_b16 v[184:185], v146 offset:12288
	ds_read_b64_tr_b16 v[186:187], v146 offset:13312
	ds_read_b64_tr_b16 v[188:189], v146 offset:12800
	ds_read_b64_tr_b16 v[190:191], v146 offset:13824
	v_mfma_f32_32x32x16_bf16 v[112:127], v[60:63], v[140:143], v[112:127]
	ds_read_b64_tr_b16 v[192:193], v146 offset:14336
	ds_read_b64_tr_b16 v[194:195], v146 offset:15360
	ds_read_b64_tr_b16 v[196:197], v146 offset:14848
	ds_read_b64_tr_b16 v[198:199], v146 offset:15872
	v_exp_f32_e32 v96, v96
	v_exp_f32_e32 v97, v97
	v_exp_f32_e32 v98, v98
	v_exp_f32_e32 v99, v99
	v_exp_f32_e32 v100, v100
	v_exp_f32_e32 v101, v101
	v_exp_f32_e32 v102, v102
	v_exp_f32_e32 v103, v103
	v_cvt_pk_bf16_f32 v162, v96, v97
	v_cvt_pk_bf16_f32 v163, v98, v99
	v_cvt_pk_bf16_f32 v164, v100, v101
	v_cvt_pk_bf16_f32 v165, v102, v103
	v_pk_add_f32 v[128:129], v[128:129], v[96:97]
	v_pk_add_f32 v[128:129], v[128:129], v[98:99]
	v_pk_add_f32 v[128:129], v[128:129], v[100:101]
	v_pk_add_f32 v[128:129], v[128:129], v[102:103]
	s_waitcnt lgkmcnt(12)
	v_mfma_f32_32x32x16_bf16 v[0:15], v[162:165], v[168:171], v[0:15]
	v_exp_f32_e32 v104, v104
	v_exp_f32_e32 v105, v105
	v_exp_f32_e32 v106, v106
	v_exp_f32_e32 v107, v107
	v_mfma_f32_32x32x16_bf16 v[16:31], v[162:165], v[172:175], v[16:31]
	v_exp_f32_e32 v108, v108
	v_exp_f32_e32 v109, v109
	v_exp_f32_e32 v110, v110
	v_exp_f32_e32 v111, v111
	v_cvt_pk_bf16_f32 v162, v104, v105
	v_cvt_pk_bf16_f32 v163, v106, v107
	v_cvt_pk_bf16_f32 v164, v108, v109
	v_cvt_pk_bf16_f32 v165, v110, v111
	v_pk_add_f32 v[128:129], v[128:129], v[104:105]
	v_pk_add_f32 v[128:129], v[128:129], v[106:107]
	v_pk_add_f32 v[128:129], v[128:129], v[108:109]
	v_pk_add_f32 v[128:129], v[128:129], v[110:111]
	s_waitcnt lgkmcnt(8)
	v_mfma_f32_32x32x16_bf16 v[0:15], v[162:165], v[176:179], v[0:15]
	v_exp_f32_e32 v112, v112
	v_exp_f32_e32 v113, v113
	v_exp_f32_e32 v114, v114
	v_exp_f32_e32 v115, v115
	v_mfma_f32_32x32x16_bf16 v[16:31], v[162:165], v[180:183], v[16:31]
	v_mfma_f32_32x32x16_bf16 v[96:111], v[48:51], v[150:153], v[64:79]
	v_exp_f32_e32 v116, v116
	v_exp_f32_e32 v117, v117
	v_exp_f32_e32 v118, v118
	v_exp_f32_e32 v119, v119
	v_mfma_f32_32x32x16_bf16 v[96:111], v[52:55], v[154:157], v[96:111]
	v_cvt_pk_bf16_f32 v162, v112, v113
	v_cvt_pk_bf16_f32 v163, v114, v115
	v_cvt_pk_bf16_f32 v164, v116, v117
	v_cvt_pk_bf16_f32 v165, v118, v119
	v_pk_add_f32 v[128:129], v[128:129], v[112:113]
	v_pk_add_f32 v[128:129], v[128:129], v[114:115]
	v_pk_add_f32 v[128:129], v[128:129], v[116:117]
	v_pk_add_f32 v[128:129], v[128:129], v[118:119]
	s_waitcnt lgkmcnt(4)
; #define AT_LOAD(K0, K1, V0, V1, T) do { const size_t e_ = (size_t)(128 * (T) + sr) * 64 + sc; \
;         K0 = *(const bf16x8*)(kcp + e_); V0 = *(const bf16x8*)(vcp + e_); K1 = *(const bf16x8*)(kcp + e_ + 64 * 64); V1 = *(const bf16x8*)(vcp + e_ + 64 * 64); } while (0)
; #define AT_STORE(K0, K1, V0, V1, BUF) do { *(LAS bf16x8*)(lds + AT_K + (BUF) * AT_KB + kst0) = K0; *(LAS bf16x8*)(lds + AT_K + (BUF) * AT_KB + kst1) = K1; \
;         *(LAS bf16x8*)(lds + AT_V + (BUF) * AT_VB + vst0) = V0; *(LAS bf16x8*)(lds + AT_V + (BUF) * AT_VB + vst1) = V1; } while (0)
; template <int VAR>
; __device__ __forceinline__ void attn_unit(const Args& a, int l, int b, int h, int qrow0  , bool ctxu, const bf16* Z, bf16* Y, LAS unsigned char* lds) {
;     ...
;     for (int t = 0; t < NT; t += 2) {
;         __syncthreads();
;         if (t + 2 < NT) AT_LOAD(ka0, ka1, va0, va1, t + 2);
;         attn_tile(Kb0, vb0, q0, q1, negm, m, o0, o1, lacc, t == 0, wsf, r32, hi);
;         AT_STORE(kb0, kb1, vb0_, vb1_, 1);
;         __syncthreads();
;         if (t + 3 < NT) AT_LOAD(kb0, kb1, vb0_, vb1_, t + 3);
;         attn_tile(Kb0 + AT_KB, vb0 + AT_VB, q0, q1, negm, m, o0, o1, lacc, false, wsf, r32, hi);
;         if (t + 2 < NT) AT_STORE(ka0, ka1, va0, va1, 0);
	v_mfma_f32_32x32x16_bf16 v[0:15], v[162:165], v[184:187], v[0:15]
	v_exp_f32_e32 v120, v120
	v_exp_f32_e32 v121, v121
	v_exp_f32_e32 v122, v122
	v_exp_f32_e32 v123, v123
	v_mfma_f32_32x32x16_bf16 v[16:31], v[162:165], v[188:191], v[16:31]
	v_exp_f32_e32 v124, v124
	v_exp_f32_e32 v125, v125
	v_exp_f32_e32 v126, v126
	v_exp_f32_e32 v127, v127
	v_cvt_pk_bf16_f32 v162, v120, v121
	v_cvt_pk_bf16_f32 v163, v122, v123
	v_cvt_pk_bf16_f32 v164, v124, v125
	v_cvt_pk_bf16_f32 v165, v126, v127
	v_pk_add_f32 v[128:129], v[128:129], v[120:121]
	v_pk_add_f32 v[128:129], v[128:129], v[122:123]
	v_pk_add_f32 v[128:129], v[128:129], v[124:125]
	v_pk_add_f32 v[128:129], v[128:129], v[126:127]
	v_mfma_f32_32x32x16_bf16 v[112:127], v[56:59], v[150:153], v[64:79]
	v_mfma_f32_32x32x16_bf16 v[112:127], v[60:63], v[154:157], v[112:127]
	s_waitcnt lgkmcnt(0)
	v_mfma_f32_32x32x16_bf16 v[0:15], v[162:165], v[192:195], v[0:15]
	v_mfma_f32_32x32x16_bf16 v[16:31], v[162:165], v[196:199], v[16:31]
	v_exp_f32_e32 v96, v96
	v_exp_f32_e32 v97, v97
	v_exp_f32_e32 v98, v98
	v_exp_f32_e32 v99, v99
	v_exp_f32_e32 v100, v100
	v_exp_f32_e32 v101, v101
	v_exp_f32_e32 v102, v102
	v_exp_f32_e32 v103, v103
	v_cvt_pk_bf16_f32 v162, v96, v97
	v_cvt_pk_bf16_f32 v163, v98, v99
	v_cvt_pk_bf16_f32 v164, v100, v101
	v_cvt_pk_bf16_f32 v165, v102, v103
	v_pk_add_f32 v[130:131], v[130:131], v[96:97]
	v_pk_add_f32 v[130:131], v[130:131], v[98:99]
	v_pk_add_f32 v[130:131], v[130:131], v[100:101]
	v_pk_add_f32 v[130:131], v[130:131], v[102:103]
	v_mfma_f32_32x32x16_bf16 v[80:95], v[162:165], v[168:171], v[80:95]
	v_exp_f32_e32 v104, v104
	v_exp_f32_e32 v105, v105
	v_exp_f32_e32 v106, v106
	v_exp_f32_e32 v107, v107
	v_mfma_f32_32x32x16_bf16 v[200:215], v[162:165], v[172:175], v[200:215]
	v_exp_f32_e32 v108, v108
	v_exp_f32_e32 v109, v109
	v_exp_f32_e32 v110, v110
	v_exp_f32_e32 v111, v111
	v_cvt_pk_bf16_f32 v162, v104, v105
	v_cvt_pk_bf16_f32 v163, v106, v107
	v_cvt_pk_bf16_f32 v164, v108, v109
	v_cvt_pk_bf16_f32 v165, v110, v111
	v_pk_add_f32 v[130:131], v[130:131], v[104:105]
	v_pk_add_f32 v[130:131], v[130:131], v[106:107]
	v_pk_add_f32 v[130:131], v[130:131], v[108:109]
	v_pk_add_f32 v[130:131], v[130:131], v[110:111]
	v_mfma_f32_32x32x16_bf16 v[80:95], v[162:165], v[176:179], v[80:95]
	v_exp_f32_e32 v112, v112
	v_exp_f32_e32 v113, v113
	v_exp_f32_e32 v114, v114
	v_exp_f32_e32 v115, v115
	v_mfma_f32_32x32x16_bf16 v[200:215], v[162:165], v[180:183], v[200:215]
	v_exp_f32_e32 v116, v116
	v_exp_f32_e32 v117, v117
	v_exp_f32_e32 v118, v118
	v_exp_f32_e32 v119, v119
	v_cvt_pk_bf16_f32 v162, v112, v113
	v_cvt_pk_bf16_f32 v163, v114, v115
	v_cvt_pk_bf16_f32 v164, v116, v117
	v_cvt_pk_bf16_f32 v165, v118, v119
	v_pk_add_f32 v[130:131], v[130:131], v[112:113]
	v_pk_add_f32 v[130:131], v[130:131], v[114:115]
	v_pk_add_f32 v[130:131], v[130:131], v[116:117]
	v_pk_add_f32 v[130:131], v[130:131], v[118:119]
	v_mfma_f32_32x32x16_bf16 v[80:95], v[162:165], v[184:187], v[80:95]
	v_exp_f32_e32 v120, v120
	v_exp_f32_e32 v121, v121
	v_exp_f32_e32 v122, v122
	v_exp_f32_e32 v123, v123
	v_mfma_f32_32x32x16_bf16 v[200:215], v[162:165], v[188:191], v[200:215]
	v_exp_f32_e32 v124, v124
	v_exp_f32_e32 v125, v125
	v_exp_f32_e32 v126, v126
	v_exp_f32_e32 v127, v127
	v_cvt_pk_bf16_f32 v162, v120, v121
	v_cvt_pk_bf16_f32 v163, v122, v123
	v_cvt_pk_bf16_f32 v164, v124, v125
	v_cvt_pk_bf16_f32 v165, v126, v127
	v_pk_add_f32 v[130:131], v[130:131], v[120:121]
	v_pk_add_f32 v[130:131], v[130:131], v[122:123]
	v_pk_add_f32 v[130:131], v[130:131], v[124:125]
	v_pk_add_f32 v[130:131], v[130:131], v[126:127]
	s_waitcnt vmcnt(4)
	s_waitcnt lgkmcnt(0)
	s_barrier
	s_cmp_eq_u32 s33, 21
	s_cbranch_scc1 .Lat_ndF1
	s_add_u32 m0, s51, 0x0
	s_nop 0
	global_load_lds_dwordx4 v158, s[36:37]
	s_add_u32 m0, s51, 0x2000
	s_nop 0
	global_load_lds_dwordx4 v159, s[36:37]
	s_add_u32 m0, s51, 0xc000
	s_nop 0
	global_load_lds_dwordx4 v160, s[48:49]
	s_add_u32 m0, s51, 0xe000
	s_nop 0
	global_load_lds_dwordx4 v161, s[48:49]
	s_add_u32 s36, s36, 0x4000
	s_addc_u32 s37, s37, 0
	s_add_u32 s48, s48, 0x4000
	s_addc_u32 s49, s49, 0
.Lat_ndF1:
	ds_read_b128 v[48:51], v144 offset:16384
	ds_read_b128 v[52:55], v145 offset:16384
	ds_read_b128 v[56:59], v144 offset:20480
	ds_read_b128 v[60:63], v145 offset:20480
	v_mfma_f32_32x32x16_bf16 v[80:95], v[162:165], v[192:195], v[80:95]
	v_mfma_f32_32x32x16_bf16 v[200:215], v[162:165], v[196:199], v[200:215]
	s_waitcnt lgkmcnt(0)
	v_mfma_f32_32x32x16_bf16 v[96:111], v[48:51], v[136:139], v[32:47]
	ds_read_b64_tr_b16 v[168:169], v146 offset:16384
	ds_read_b64_tr_b16 v[170:171], v146 offset:17408
	ds_read_b64_tr_b16 v[172:173], v146 offset:16896
	ds_read_b64_tr_b16 v[174:175], v146 offset:17920
	v_mfma_f32_32x32x16_bf16 v[96:111], v[52:55], v[140:143], v[96:111]
	ds_read_b64_tr_b16 v[176:177], v146 offset:18432
	ds_read_b64_tr_b16 v[178:179], v146 offset:19456
	ds_read_b64_tr_b16 v[180:181], v146 offset:18944
	ds_read_b64_tr_b16 v[182:183], v146 offset:19968
	v_mfma_f32_32x32x16_bf16 v[112:127], v[56:59], v[136:139], v[32:47]
	ds_read_b64_tr_b16 v[184:185], v146 offset:20480
	ds_read_b64_tr_b16 v[186:187], v146 offset:21504
	ds_read_b64_tr_b16 v[188:189], v146 offset:20992
	ds_read_b64_tr_b16 v[190:191], v146 offset:22016
	v_mfma_f32_32x32x16_bf16 v[112:127], v[60:63], v[140:143], v[112:127]
	ds_read_b64_tr_b16 v[192:193], v146 offset:22528
	ds_read_b64_tr_b16 v[194:195], v146 offset:23552
	ds_read_b64_tr_b16 v[196:197], v146 offset:23040
	ds_read_b64_tr_b16 v[198:199], v146 offset:24064
	v_exp_f32_e32 v96, v96
	v_exp_f32_e32 v97, v97
	v_exp_f32_e32 v98, v98
	v_exp_f32_e32 v99, v99
	v_exp_f32_e32 v100, v100
	v_exp_f32_e32 v101, v101
	v_exp_f32_e32 v102, v102
	v_exp_f32_e32 v103, v103
	v_cvt_pk_bf16_f32 v162, v96, v97
	v_cvt_pk_bf16_f32 v163, v98, v99
	v_cvt_pk_bf16_f32 v164, v100, v101
	v_cvt_pk_bf16_f32 v165, v102, v103
	v_pk_add_f32 v[128:129], v[128:129], v[96:97]
	v_pk_add_f32 v[128:129], v[128:129], v[98:99]
	v_pk_add_f32 v[128:129], v[128:129], v[100:101]
	v_pk_add_f32 v[128:129], v[128:129], v[102:103]
	s_waitcnt lgkmcnt(12)
	v_mfma_f32_32x32x16_bf16 v[0:15], v[162:165], v[168:171], v[0:15]
	v_exp_f32_e32 v104, v104
	v_exp_f32_e32 v105, v105
	v_exp_f32_e32 v106, v106
	v_exp_f32_e32 v107, v107
	v_mfma_f32_32x32x16_bf16 v[16:31], v[162:165], v[172:175], v[16:31]
	v_exp_f32_e32 v108, v108
	v_exp_f32_e32 v109, v109
	v_exp_f32_e32 v110, v110
	v_exp_f32_e32 v111, v111
	v_cvt_pk_bf16_f32 v162, v104, v105
	v_cvt_pk_bf16_f32 v163, v106, v107
	v_cvt_pk_bf16_f32 v164, v108, v109
	v_cvt_pk_bf16_f32 v165, v110, v111
	v_pk_add_f32 v[128:129], v[128:129], v[104:105]
	v_pk_add_f32 v[128:129], v[128:129], v[106:107]
	v_pk_add_f32 v[128:129], v[128:129], v[108:109]
	v_pk_add_f32 v[128:129], v[128:129], v[110:111]
	s_waitcnt lgkmcnt(8)
	v_mfma_f32_32x32x16_bf16 v[0:15], v[162:165], v[176:179], v[0:15]
	v_exp_f32_e32 v112, v112
	v_exp_f32_e32 v113, v113
	v_exp_f32_e32 v114, v114
	v_exp_f32_e32 v115, v115
	v_mfma_f32_32x32x16_bf16 v[16:31], v[162:165], v[180:183], v[16:31]
	v_mfma_f32_32x32x16_bf16 v[96:111], v[48:51], v[150:153], v[64:79]
	v_exp_f32_e32 v116, v116
	v_exp_f32_e32 v117, v117
	v_exp_f32_e32 v118, v118
	v_exp_f32_e32 v119, v119
	v_mfma_f32_32x32x16_bf16 v[96:111], v[52:55], v[154:157], v[96:111]
	v_cvt_pk_bf16_f32 v162, v112, v113
	v_cvt_pk_bf16_f32 v163, v114, v115
	v_cvt_pk_bf16_f32 v164, v116, v117
	v_cvt_pk_bf16_f32 v165, v118, v119
	v_pk_add_f32 v[128:129], v[128:129], v[112:113]
	v_pk_add_f32 v[128:129], v[128:129], v[114:115]
	v_pk_add_f32 v[128:129], v[128:129], v[116:117]
	v_pk_add_f32 v[128:129], v[128:129], v[118:119]
	s_waitcnt lgkmcnt(4)
	v_mfma_f32_32x32x16_bf16 v[0:15], v[162:165], v[184:187], v[0:15]
	v_exp_f32_e32 v120, v120
	v_exp_f32_e32 v121, v121
	v_exp_f32_e32 v122, v122
	v_exp_f32_e32 v123, v123
	v_mfma_f32_32x32x16_bf16 v[16:31], v[162:165], v[188:191], v[16:31]
	v_exp_f32_e32 v124, v124
	v_exp_f32_e32 v125, v125
	v_exp_f32_e32 v126, v126
	v_exp_f32_e32 v127, v127
	v_cvt_pk_bf16_f32 v162, v120, v121
	v_cvt_pk_bf16_f32 v163, v122, v123
	v_cvt_pk_bf16_f32 v164, v124, v125
	v_cvt_pk_bf16_f32 v165, v126, v127
	v_pk_add_f32 v[128:129], v[128:129], v[120:121]
	v_pk_add_f32 v[128:129], v[128:129], v[122:123]
	v_pk_add_f32 v[128:129], v[128:129], v[124:125]
	v_pk_add_f32 v[128:129], v[128:129], v[126:127]
	v_mfma_f32_32x32x16_bf16 v[112:127], v[56:59], v[150:153], v[64:79]
	v_mfma_f32_32x32x16_bf16 v[112:127], v[60:63], v[154:157], v[112:127]
	s_waitcnt lgkmcnt(0)
	v_mfma_f32_32x32x16_bf16 v[0:15], v[162:165], v[192:195], v[0:15]
	v_mfma_f32_32x32x16_bf16 v[16:31], v[162:165], v[196:199], v[16:31]
	ds_read_b128 v[48:51], v144 offset:24576
	ds_read_b128 v[52:55], v145 offset:24576
	ds_read_b128 v[56:59], v144 offset:28672
	ds_read_b128 v[60:63], v145 offset:28672
	v_exp_f32_e32 v96, v96
	v_exp_f32_e32 v97, v97
	v_exp_f32_e32 v98, v98
	v_exp_f32_e32 v99, v99
	v_exp_f32_e32 v100, v100
	v_exp_f32_e32 v101, v101
	v_exp_f32_e32 v102, v102
	v_exp_f32_e32 v103, v103
	v_cvt_pk_bf16_f32 v162, v96, v97
	v_cvt_pk_bf16_f32 v163, v98, v99
	v_cvt_pk_bf16_f32 v164, v100, v101
	v_cvt_pk_bf16_f32 v165, v102, v103
	v_pk_add_f32 v[130:131], v[130:131], v[96:97]
	v_pk_add_f32 v[130:131], v[130:131], v[98:99]
	v_pk_add_f32 v[130:131], v[130:131], v[100:101]
	v_pk_add_f32 v[130:131], v[130:131], v[102:103]
	v_mfma_f32_32x32x16_bf16 v[80:95], v[162:165], v[168:171], v[80:95]
	v_exp_f32_e32 v104, v104
	v_exp_f32_e32 v105, v105
	v_exp_f32_e32 v106, v106
	v_exp_f32_e32 v107, v107
	v_mfma_f32_32x32x16_bf16 v[200:215], v[162:165], v[172:175], v[200:215]
	v_exp_f32_e32 v108, v108
	v_exp_f32_e32 v109, v109
	v_exp_f32_e32 v110, v110
	v_exp_f32_e32 v111, v111
	v_cvt_pk_bf16_f32 v162, v104, v105
	v_cvt_pk_bf16_f32 v163, v106, v107
	v_cvt_pk_bf16_f32 v164, v108, v109
	v_cvt_pk_bf16_f32 v165, v110, v111
	v_pk_add_f32 v[130:131], v[130:131], v[104:105]
	v_pk_add_f32 v[130:131], v[130:131], v[106:107]
	v_pk_add_f32 v[130:131], v[130:131], v[108:109]
	v_pk_add_f32 v[130:131], v[130:131], v[110:111]
	v_mfma_f32_32x32x16_bf16 v[80:95], v[162:165], v[176:179], v[80:95]
	v_exp_f32_e32 v112, v112
	v_exp_f32_e32 v113, v113
	v_exp_f32_e32 v114, v114
	v_exp_f32_e32 v115, v115
	v_mfma_f32_32x32x16_bf16 v[200:215], v[162:165], v[180:183], v[200:215]
	v_exp_f32_e32 v116, v116
	v_exp_f32_e32 v117, v117
	v_exp_f32_e32 v118, v118
	v_exp_f32_e32 v119, v119
	v_cvt_pk_bf16_f32 v162, v112, v113
	v_cvt_pk_bf16_f32 v163, v114, v115
	v_cvt_pk_bf16_f32 v164, v116, v117
	v_cvt_pk_bf16_f32 v165, v118, v119
	v_pk_add_f32 v[130:131], v[130:131], v[112:113]
	v_pk_add_f32 v[130:131], v[130:131], v[114:115]
	v_pk_add_f32 v[130:131], v[130:131], v[116:117]
	v_pk_add_f32 v[130:131], v[130:131], v[118:119]
	v_mfma_f32_32x32x16_bf16 v[80:95], v[162:165], v[184:187], v[80:95]
	v_exp_f32_e32 v120, v120
	v_exp_f32_e32 v121, v121
	v_exp_f32_e32 v122, v122
	v_exp_f32_e32 v123, v123
	v_mfma_f32_32x32x16_bf16 v[200:215], v[162:165], v[188:191], v[200:215]
	v_exp_f32_e32 v124, v124
	v_exp_f32_e32 v125, v125
	v_exp_f32_e32 v126, v126
	v_exp_f32_e32 v127, v127
	v_cvt_pk_bf16_f32 v162, v120, v121
	v_cvt_pk_bf16_f32 v163, v122, v123
	v_cvt_pk_bf16_f32 v164, v124, v125
	v_cvt_pk_bf16_f32 v165, v126, v127
	v_pk_add_f32 v[130:131], v[130:131], v[120:121]
	v_pk_add_f32 v[130:131], v[130:131], v[122:123]
	v_pk_add_f32 v[130:131], v[130:131], v[124:125]
	v_pk_add_f32 v[130:131], v[130:131], v[126:127]
	v_mfma_f32_32x32x16_bf16 v[80:95], v[162:165], v[192:195], v[80:95]
	v_mfma_f32_32x32x16_bf16 v[200:215], v[162:165], v[196:199], v[200:215]
	s_waitcnt lgkmcnt(0)
	v_mfma_f32_32x32x16_bf16 v[96:111], v[48:51], v[136:139], v[32:47]
	ds_read_b64_tr_b16 v[168:169], v146 offset:24576
	ds_read_b64_tr_b16 v[170:171], v146 offset:25600
	ds_read_b64_tr_b16 v[172:173], v146 offset:25088
	ds_read_b64_tr_b16 v[174:175], v146 offset:26112
	v_mfma_f32_32x32x16_bf16 v[96:111], v[52:55], v[140:143], v[96:111]
	ds_read_b64_tr_b16 v[176:177], v146 offset:26624
	ds_read_b64_tr_b16 v[178:179], v146 offset:27648
	ds_read_b64_tr_b16 v[180:181], v146 offset:27136
	ds_read_b64_tr_b16 v[182:183], v146 offset:28160
	v_mfma_f32_32x32x16_bf16 v[112:127], v[56:59], v[136:139], v[32:47]
	ds_read_b64_tr_b16 v[184:185], v146 offset:28672
	ds_read_b64_tr_b16 v[186:187], v146 offset:29696
	ds_read_b64_tr_b16 v[188:189], v146 offset:29184
	ds_read_b64_tr_b16 v[190:191], v146 offset:30208
	v_mfma_f32_32x32x16_bf16 v[112:127], v[60:63], v[140:143], v[112:127]
	ds_read_b64_tr_b16 v[192:193], v146 offset:30720
	ds_read_b64_tr_b16 v[194:195], v146 offset:31744
	ds_read_b64_tr_b16 v[196:197], v146 offset:31232
	ds_read_b64_tr_b16 v[198:199], v146 offset:32256
	v_exp_f32_e32 v96, v96
	v_exp_f32_e32 v97, v97
	v_exp_f32_e32 v98, v98
	v_exp_f32_e32 v99, v99
	v_exp_f32_e32 v100, v100
	v_exp_f32_e32 v101, v101
	v_exp_f32_e32 v102, v102
	v_exp_f32_e32 v103, v103
	v_cvt_pk_bf16_f32 v162, v96, v97
	v_cvt_pk_bf16_f32 v163, v98, v99
	v_cvt_pk_bf16_f32 v164, v100, v101
	v_cvt_pk_bf16_f32 v165, v102, v103
	v_pk_add_f32 v[128:129], v[128:129], v[96:97]
	v_pk_add_f32 v[128:129], v[128:129], v[98:99]
	v_pk_add_f32 v[128:129], v[128:129], v[100:101]
	v_pk_add_f32 v[128:129], v[128:129], v[102:103]
	s_waitcnt lgkmcnt(12)
	v_mfma_f32_32x32x16_bf16 v[0:15], v[162:165], v[168:171], v[0:15]
	v_exp_f32_e32 v104, v104
	v_exp_f32_e32 v105, v105
	v_exp_f32_e32 v106, v106
	v_exp_f32_e32 v107, v107
	v_mfma_f32_32x32x16_bf16 v[16:31], v[162:165], v[172:175], v[16:31]
	v_exp_f32_e32 v108, v108
	v_exp_f32_e32 v109, v109
	v_exp_f32_e32 v110, v110
	v_exp_f32_e32 v111, v111
	v_cvt_pk_bf16_f32 v162, v104, v105
	v_cvt_pk_bf16_f32 v163, v106, v107
	v_cvt_pk_bf16_f32 v164, v108, v109
	v_cvt_pk_bf16_f32 v165, v110, v111
	v_pk_add_f32 v[128:129], v[128:129], v[104:105]
	v_pk_add_f32 v[128:129], v[128:129], v[106:107]
	v_pk_add_f32 v[128:129], v[128:129], v[108:109]
	v_pk_add_f32 v[128:129], v[128:129], v[110:111]
	s_waitcnt lgkmcnt(8)
	v_mfma_f32_32x32x16_bf16 v[0:15], v[162:165], v[176:179], v[0:15]
	v_exp_f32_e32 v112, v112
	v_exp_f32_e32 v113, v113
	v_exp_f32_e32 v114, v114
	v_exp_f32_e32 v115, v115
	v_mfma_f32_32x32x16_bf16 v[16:31], v[162:165], v[180:183], v[16:31]
	v_mfma_f32_32x32x16_bf16 v[96:111], v[48:51], v[150:153], v[64:79]
	v_exp_f32_e32 v116, v116
	v_exp_f32_e32 v117, v117
	v_exp_f32_e32 v118, v118
	v_exp_f32_e32 v119, v119
	v_mfma_f32_32x32x16_bf16 v[96:111], v[52:55], v[154:157], v[96:111]
	v_cvt_pk_bf16_f32 v162, v112, v113
	v_cvt_pk_bf16_f32 v163, v114, v115
	v_cvt_pk_bf16_f32 v164, v116, v117
	v_cvt_pk_bf16_f32 v165, v118, v119
	v_pk_add_f32 v[128:129], v[128:129], v[112:113]
	v_pk_add_f32 v[128:129], v[128:129], v[114:115]
	v_pk_add_f32 v[128:129], v[128:129], v[116:117]
	v_pk_add_f32 v[128:129], v[128:129], v[118:119]
	s_waitcnt lgkmcnt(4)
	v_mfma_f32_32x32x16_bf16 v[0:15], v[162:165], v[184:187], v[0:15]
	v_exp_f32_e32 v120, v120
	v_exp_f32_e32 v121, v121
	v_exp_f32_e32 v122, v122
	v_exp_f32_e32 v123, v123
	v_mfma_f32_32x32x16_bf16 v[16:31], v[162:165], v[188:191], v[16:31]
	v_exp_f32_e32 v124, v124
	v_exp_f32_e32 v125, v125
	v_exp_f32_e32 v126, v126
	v_exp_f32_e32 v127, v127
	v_cvt_pk_bf16_f32 v162, v120, v121
	v_cvt_pk_bf16_f32 v163, v122, v123
	v_cvt_pk_bf16_f32 v164, v124, v125
	v_cvt_pk_bf16_f32 v165, v126, v127
	v_pk_add_f32 v[128:129], v[128:129], v[120:121]
	v_pk_add_f32 v[128:129], v[128:129], v[122:123]
	v_pk_add_f32 v[128:129], v[128:129], v[124:125]
	v_pk_add_f32 v[128:129], v[128:129], v[126:127]
	v_mfma_f32_32x32x16_bf16 v[112:127], v[56:59], v[150:153], v[64:79]
	v_mfma_f32_32x32x16_bf16 v[112:127], v[60:63], v[154:157], v[112:127]
	s_waitcnt lgkmcnt(0)
	v_mfma_f32_32x32x16_bf16 v[0:15], v[162:165], v[192:195], v[0:15]
	v_mfma_f32_32x32x16_bf16 v[16:31], v[162:165], v[196:199], v[16:31]
	v_exp_f32_e32 v96, v96
	v_exp_f32_e32 v97, v97
	v_exp_f32_e32 v98, v98
	v_exp_f32_e32 v99, v99
	v_exp_f32_e32 v100, v100
	v_exp_f32_e32 v101, v101
	v_exp_f32_e32 v102, v102
	v_exp_f32_e32 v103, v103
	v_cvt_pk_bf16_f32 v162, v96, v97
	v_cvt_pk_bf16_f32 v163, v98, v99
	v_cvt_pk_bf16_f32 v164, v100, v101
	v_cvt_pk_bf16_f32 v165, v102, v103
	v_pk_add_f32 v[130:131], v[130:131], v[96:97]
	v_pk_add_f32 v[130:131], v[130:131], v[98:99]
	v_pk_add_f32 v[130:131], v[130:131], v[100:101]
	v_pk_add_f32 v[130:131], v[130:131], v[102:103]
	v_mfma_f32_32x32x16_bf16 v[80:95], v[162:165], v[168:171], v[80:95]
	v_exp_f32_e32 v104, v104
	v_exp_f32_e32 v105, v105
	v_exp_f32_e32 v106, v106
	v_exp_f32_e32 v107, v107
	v_mfma_f32_32x32x16_bf16 v[200:215], v[162:165], v[172:175], v[200:215]
	v_exp_f32_e32 v108, v108
	v_exp_f32_e32 v109, v109
	v_exp_f32_e32 v110, v110
	v_exp_f32_e32 v111, v111
	v_cvt_pk_bf16_f32 v162, v104, v105
	v_cvt_pk_bf16_f32 v163, v106, v107
	v_cvt_pk_bf16_f32 v164, v108, v109
	v_cvt_pk_bf16_f32 v165, v110, v111
	v_pk_add_f32 v[130:131], v[130:131], v[104:105]
	v_pk_add_f32 v[130:131], v[130:131], v[106:107]
	v_pk_add_f32 v[130:131], v[130:131], v[108:109]
	v_pk_add_f32 v[130:131], v[130:131], v[110:111]
	v_mfma_f32_32x32x16_bf16 v[80:95], v[162:165], v[176:179], v[80:95]
	v_exp_f32_e32 v112, v112
	v_exp_f32_e32 v113, v113
	v_exp_f32_e32 v114, v114
	v_exp_f32_e32 v115, v115
	v_mfma_f32_32x32x16_bf16 v[200:215], v[162:165], v[180:183], v[200:215]
	v_exp_f32_e32 v116, v116
	v_exp_f32_e32 v117, v117
	v_exp_f32_e32 v118, v118
	v_exp_f32_e32 v119, v119
	v_cvt_pk_bf16_f32 v162, v112, v113
	v_cvt_pk_bf16_f32 v163, v114, v115
	v_cvt_pk_bf16_f32 v164, v116, v117
	v_cvt_pk_bf16_f32 v165, v118, v119
	v_pk_add_f32 v[130:131], v[130:131], v[112:113]
	v_pk_add_f32 v[130:131], v[130:131], v[114:115]
	v_pk_add_f32 v[130:131], v[130:131], v[116:117]
	v_pk_add_f32 v[130:131], v[130:131], v[118:119]
	v_mfma_f32_32x32x16_bf16 v[80:95], v[162:165], v[184:187], v[80:95]
	v_exp_f32_e32 v120, v120
	v_exp_f32_e32 v121, v121
	v_exp_f32_e32 v122, v122
	v_exp_f32_e32 v123, v123
	v_mfma_f32_32x32x16_bf16 v[200:215], v[162:165], v[188:191], v[200:215]
	v_exp_f32_e32 v124, v124
	v_exp_f32_e32 v125, v125
	v_exp_f32_e32 v126, v126
	v_exp_f32_e32 v127, v127
	v_cvt_pk_bf16_f32 v162, v120, v121
	v_cvt_pk_bf16_f32 v163, v122, v123
	v_cvt_pk_bf16_f32 v164, v124, v125
	v_cvt_pk_bf16_f32 v165, v126, v127
	v_pk_add_f32 v[130:131], v[130:131], v[120:121]
	v_pk_add_f32 v[130:131], v[130:131], v[122:123]
	v_pk_add_f32 v[130:131], v[130:131], v[124:125]
	v_pk_add_f32 v[130:131], v[130:131], v[126:127]
	s_cmp_eq_u32 s33, 21
	s_cbranch_scc1 .Lat_w0F3
	s_waitcnt vmcnt(4)
	s_branch .Lat_wdF3

.Lat_ndF3:
	ds_read_b128 v[48:51], v144 offset:32768
	ds_read_b128 v[52:55], v145 offset:32768
	ds_read_b128 v[56:59], v144 offset:36864
	ds_read_b128 v[60:63], v145 offset:36864
	v_mfma_f32_32x32x16_bf16 v[80:95], v[162:165], v[192:195], v[80:95]
	v_mfma_f32_32x32x16_bf16 v[200:215], v[162:165], v[196:199], v[200:215]
	s_waitcnt lgkmcnt(0)
	v_mfma_f32_32x32x16_bf16 v[96:111], v[48:51], v[136:139], v[32:47]
	ds_read_b64_tr_b16 v[168:169], v146 offset:32768
	ds_read_b64_tr_b16 v[170:171], v146 offset:33792
	ds_read_b64_tr_b16 v[172:173], v146 offset:33280
	ds_read_b64_tr_b16 v[174:175], v146 offset:34304
	v_mfma_f32_32x32x16_bf16 v[96:111], v[52:55], v[140:143], v[96:111]
	ds_read_b64_tr_b16 v[176:177], v146 offset:34816
	ds_read_b64_tr_b16 v[178:179], v146 offset:35840
	ds_read_b64_tr_b16 v[180:181], v146 offset:35328
	ds_read_b64_tr_b16 v[182:183], v146 offset:36352
	v_mfma_f32_32x32x16_bf16 v[112:127], v[56:59], v[136:139], v[32:47]
	ds_read_b64_tr_b16 v[184:185], v146 offset:36864
	ds_read_b64_tr_b16 v[186:187], v146 offset:37888
	ds_read_b64_tr_b16 v[188:189], v146 offset:37376
	ds_read_b64_tr_b16 v[190:191], v146 offset:38400
	v_mfma_f32_32x32x16_bf16 v[112:127], v[60:63], v[140:143], v[112:127]
	ds_read_b64_tr_b16 v[192:193], v146 offset:38912
	ds_read_b64_tr_b16 v[194:195], v146 offset:39936
	ds_read_b64_tr_b16 v[196:197], v146 offset:39424
	ds_read_b64_tr_b16 v[198:199], v146 offset:40448
	v_exp_f32_e32 v96, v96
	v_exp_f32_e32 v97, v97
	v_exp_f32_e32 v98, v98
	v_exp_f32_e32 v99, v99
	v_exp_f32_e32 v100, v100
	v_exp_f32_e32 v101, v101
	v_exp_f32_e32 v102, v102
	v_exp_f32_e32 v103, v103
	v_cvt_pk_bf16_f32 v162, v96, v97
	v_cvt_pk_bf16_f32 v163, v98, v99
	v_cvt_pk_bf16_f32 v164, v100, v101
	v_cvt_pk_bf16_f32 v165, v102, v103
	v_pk_add_f32 v[128:129], v[128:129], v[96:97]
	v_pk_add_f32 v[128:129], v[128:129], v[98:99]
	v_pk_add_f32 v[128:129], v[128:129], v[100:101]
	v_pk_add_f32 v[128:129], v[128:129], v[102:103]
	s_waitcnt lgkmcnt(12)
	v_mfma_f32_32x32x16_bf16 v[0:15], v[162:165], v[168:171], v[0:15]
	v_exp_f32_e32 v104, v104
	v_exp_f32_e32 v105, v105
	v_exp_f32_e32 v106, v106
	v_exp_f32_e32 v107, v107
	v_mfma_f32_32x32x16_bf16 v[16:31], v[162:165], v[172:175], v[16:31]
	v_exp_f32_e32 v108, v108
	v_exp_f32_e32 v109, v109
	v_exp_f32_e32 v110, v110
	v_exp_f32_e32 v111, v111
	v_cvt_pk_bf16_f32 v162, v104, v105
	v_cvt_pk_bf16_f32 v163, v106, v107
	v_cvt_pk_bf16_f32 v164, v108, v109
	v_cvt_pk_bf16_f32 v165, v110, v111
	v_pk_add_f32 v[128:129], v[128:129], v[104:105]
	v_pk_add_f32 v[128:129], v[128:129], v[106:107]
	v_pk_add_f32 v[128:129], v[128:129], v[108:109]
	v_pk_add_f32 v[128:129], v[128:129], v[110:111]
	s_waitcnt lgkmcnt(8)
	v_mfma_f32_32x32x16_bf16 v[0:15], v[162:165], v[176:179], v[0:15]
	v_exp_f32_e32 v112, v112
	v_exp_f32_e32 v113, v113
	v_exp_f32_e32 v114, v114
	v_exp_f32_e32 v115, v115
	v_mfma_f32_32x32x16_bf16 v[16:31], v[162:165], v[180:183], v[16:31]
	v_mfma_f32_32x32x16_bf16 v[96:111], v[48:51], v[150:153], v[64:79]
	v_exp_f32_e32 v116, v116
	v_exp_f32_e32 v117, v117
	v_exp_f32_e32 v118, v118
	v_exp_f32_e32 v119, v119
	v_mfma_f32_32x32x16_bf16 v[96:111], v[52:55], v[154:157], v[96:111]
	v_cvt_pk_bf16_f32 v162, v112, v113
	v_cvt_pk_bf16_f32 v163, v114, v115
	v_cvt_pk_bf16_f32 v164, v116, v117
	v_cvt_pk_bf16_f32 v165, v118, v119
	v_pk_add_f32 v[128:129], v[128:129], v[112:113]
	v_pk_add_f32 v[128:129], v[128:129], v[114:115]
	v_pk_add_f32 v[128:129], v[128:129], v[116:117]
	v_pk_add_f32 v[128:129], v[128:129], v[118:119]
	s_waitcnt lgkmcnt(4)
	v_mfma_f32_32x32x16_bf16 v[0:15], v[162:165], v[184:187], v[0:15]
	v_exp_f32_e32 v120, v120
	v_exp_f32_e32 v121, v121
	v_exp_f32_e32 v122, v122
	v_exp_f32_e32 v123, v123
	v_mfma_f32_32x32x16_bf16 v[16:31], v[162:165], v[188:191], v[16:31]
	v_exp_f32_e32 v124, v124
	v_exp_f32_e32 v125, v125
	v_exp_f32_e32 v126, v126
	v_exp_f32_e32 v127, v127
	v_cvt_pk_bf16_f32 v162, v120, v121
	v_cvt_pk_bf16_f32 v163, v122, v123
	v_cvt_pk_bf16_f32 v164, v124, v125
	v_cvt_pk_bf16_f32 v165, v126, v127
	v_pk_add_f32 v[128:129], v[128:129], v[120:121]
	v_pk_add_f32 v[128:129], v[128:129], v[122:123]
	v_pk_add_f32 v[128:129], v[128:129], v[124:125]
	v_pk_add_f32 v[128:129], v[128:129], v[126:127]
	v_mfma_f32_32x32x16_bf16 v[112:127], v[56:59], v[150:153], v[64:79]
	v_mfma_f32_32x32x16_bf16 v[112:127], v[60:63], v[154:157], v[112:127]
	s_waitcnt lgkmcnt(0)
	v_mfma_f32_32x32x16_bf16 v[0:15], v[162:165], v[192:195], v[0:15]
	v_mfma_f32_32x32x16_bf16 v[16:31], v[162:165], v[196:199], v[16:31]
	ds_read_b128 v[48:51], v144 offset:40960
	ds_read_b128 v[52:55], v145 offset:40960
	ds_read_b128 v[56:59], v144 offset:45056
	ds_read_b128 v[60:63], v145 offset:45056
	v_exp_f32_e32 v96, v96
	v_exp_f32_e32 v97, v97
	v_exp_f32_e32 v98, v98
	v_exp_f32_e32 v99, v99
	v_exp_f32_e32 v100, v100
	v_exp_f32_e32 v101, v101
	v_exp_f32_e32 v102, v102
	v_exp_f32_e32 v103, v103
	v_cvt_pk_bf16_f32 v162, v96, v97
	v_cvt_pk_bf16_f32 v163, v98, v99
	v_cvt_pk_bf16_f32 v164, v100, v101
	v_cvt_pk_bf16_f32 v165, v102, v103
	v_pk_add_f32 v[130:131], v[130:131], v[96:97]
	v_pk_add_f32 v[130:131], v[130:131], v[98:99]
	v_pk_add_f32 v[130:131], v[130:131], v[100:101]
	v_pk_add_f32 v[130:131], v[130:131], v[102:103]
	v_mfma_f32_32x32x16_bf16 v[80:95], v[162:165], v[168:171], v[80:95]
	v_exp_f32_e32 v104, v104
	v_exp_f32_e32 v105, v105
	v_exp_f32_e32 v106, v106
	v_exp_f32_e32 v107, v107
	v_mfma_f32_32x32x16_bf16 v[200:215], v[162:165], v[172:175], v[200:215]
	v_exp_f32_e32 v108, v108
	v_exp_f32_e32 v109, v109
	v_exp_f32_e32 v110, v110
	v_exp_f32_e32 v111, v111
	v_cvt_pk_bf16_f32 v162, v104, v105
	v_cvt_pk_bf16_f32 v163, v106, v107
	v_cvt_pk_bf16_f32 v164, v108, v109
	v_cvt_pk_bf16_f32 v165, v110, v111
	v_pk_add_f32 v[130:131], v[130:131], v[104:105]
	v_pk_add_f32 v[130:131], v[130:131], v[106:107]
	v_pk_add_f32 v[130:131], v[130:131], v[108:109]
	v_pk_add_f32 v[130:131], v[130:131], v[110:111]
	v_mfma_f32_32x32x16_bf16 v[80:95], v[162:165], v[176:179], v[80:95]
	v_exp_f32_e32 v112, v112
	v_exp_f32_e32 v113, v113
	v_exp_f32_e32 v114, v114
	v_exp_f32_e32 v115, v115
	v_mfma_f32_32x32x16_bf16 v[200:215], v[162:165], v[180:183], v[200:215]
	v_exp_f32_e32 v116, v116
	v_exp_f32_e32 v117, v117
	v_exp_f32_e32 v118, v118
	v_exp_f32_e32 v119, v119
	v_cvt_pk_bf16_f32 v162, v112, v113
	v_cvt_pk_bf16_f32 v163, v114, v115
	v_cvt_pk_bf16_f32 v164, v116, v117
	v_cvt_pk_bf16_f32 v165, v118, v119
	v_pk_add_f32 v[130:131], v[130:131], v[112:113]
	v_pk_add_f32 v[130:131], v[130:131], v[114:115]
	v_pk_add_f32 v[130:131], v[130:131], v[116:117]
	v_pk_add_f32 v[130:131], v[130:131], v[118:119]
	v_mfma_f32_32x32x16_bf16 v[80:95], v[162:165], v[184:187], v[80:95]
	v_exp_f32_e32 v120, v120
	v_exp_f32_e32 v121, v121
	v_exp_f32_e32 v122, v122
	v_exp_f32_e32 v123, v123
	v_mfma_f32_32x32x16_bf16 v[200:215], v[162:165], v[188:191], v[200:215]
	v_exp_f32_e32 v124, v124
	v_exp_f32_e32 v125, v125
	v_exp_f32_e32 v126, v126
	v_exp_f32_e32 v127, v127
	v_cvt_pk_bf16_f32 v162, v120, v121
	v_cvt_pk_bf16_f32 v163, v122, v123
	v_cvt_pk_bf16_f32 v164, v124, v125
	v_cvt_pk_bf16_f32 v165, v126, v127
	v_pk_add_f32 v[130:131], v[130:131], v[120:121]
	v_pk_add_f32 v[130:131], v[130:131], v[122:123]
	v_pk_add_f32 v[130:131], v[130:131], v[124:125]
	v_pk_add_f32 v[130:131], v[130:131], v[126:127]
	v_mfma_f32_32x32x16_bf16 v[80:95], v[162:165], v[192:195], v[80:95]
	v_mfma_f32_32x32x16_bf16 v[200:215], v[162:165], v[196:199], v[200:215]
	s_waitcnt lgkmcnt(0)
	v_mfma_f32_32x32x16_bf16 v[96:111], v[48:51], v[136:139], v[32:47]
	ds_read_b64_tr_b16 v[168:169], v146 offset:40960
	ds_read_b64_tr_b16 v[170:171], v146 offset:41984
	ds_read_b64_tr_b16 v[172:173], v146 offset:41472
	ds_read_b64_tr_b16 v[174:175], v146 offset:42496
	v_mfma_f32_32x32x16_bf16 v[96:111], v[52:55], v[140:143], v[96:111]
	ds_read_b64_tr_b16 v[176:177], v146 offset:43008
	ds_read_b64_tr_b16 v[178:179], v146 offset:44032
	ds_read_b64_tr_b16 v[180:181], v146 offset:43520
	ds_read_b64_tr_b16 v[182:183], v146 offset:44544
	v_mfma_f32_32x32x16_bf16 v[112:127], v[56:59], v[136:139], v[32:47]
	ds_read_b64_tr_b16 v[184:185], v146 offset:45056
	ds_read_b64_tr_b16 v[186:187], v146 offset:46080
	ds_read_b64_tr_b16 v[188:189], v146 offset:45568
	ds_read_b64_tr_b16 v[190:191], v146 offset:46592
	v_mfma_f32_32x32x16_bf16 v[112:127], v[60:63], v[140:143], v[112:127]
	ds_read_b64_tr_b16 v[192:193], v146 offset:47104
	ds_read_b64_tr_b16 v[194:195], v146 offset:48128
	ds_read_b64_tr_b16 v[196:197], v146 offset:47616
	ds_read_b64_tr_b16 v[198:199], v146 offset:48640
	v_exp_f32_e32 v96, v96
	v_exp_f32_e32 v97, v97
	v_exp_f32_e32 v98, v98
	v_exp_f32_e32 v99, v99
	v_exp_f32_e32 v100, v100
	v_exp_f32_e32 v101, v101
	v_exp_f32_e32 v102, v102
	v_exp_f32_e32 v103, v103
	v_cvt_pk_bf16_f32 v162, v96, v97
	v_cvt_pk_bf16_f32 v163, v98, v99
	v_cvt_pk_bf16_f32 v164, v100, v101
	v_cvt_pk_bf16_f32 v165, v102, v103
	v_pk_add_f32 v[128:129], v[128:129], v[96:97]
	v_pk_add_f32 v[128:129], v[128:129], v[98:99]
	v_pk_add_f32 v[128:129], v[128:129], v[100:101]
	v_pk_add_f32 v[128:129], v[128:129], v[102:103]
	s_waitcnt lgkmcnt(12)
	v_mfma_f32_32x32x16_bf16 v[0:15], v[162:165], v[168:171], v[0:15]
	v_exp_f32_e32 v104, v104
	v_exp_f32_e32 v105, v105
	v_exp_f32_e32 v106, v106
	v_exp_f32_e32 v107, v107
	v_mfma_f32_32x32x16_bf16 v[16:31], v[162:165], v[172:175], v[16:31]
	v_exp_f32_e32 v108, v108
	v_exp_f32_e32 v109, v109
	v_exp_f32_e32 v110, v110
	v_exp_f32_e32 v111, v111
	v_cvt_pk_bf16_f32 v162, v104, v105
	v_cvt_pk_bf16_f32 v163, v106, v107
	v_cvt_pk_bf16_f32 v164, v108, v109
	v_cvt_pk_bf16_f32 v165, v110, v111
	v_pk_add_f32 v[128:129], v[128:129], v[104:105]
	v_pk_add_f32 v[128:129], v[128:129], v[106:107]
	v_pk_add_f32 v[128:129], v[128:129], v[108:109]
	v_pk_add_f32 v[128:129], v[128:129], v[110:111]
	s_waitcnt lgkmcnt(8)
	v_mfma_f32_32x32x16_bf16 v[0:15], v[162:165], v[176:179], v[0:15]
	v_exp_f32_e32 v112, v112
	v_exp_f32_e32 v113, v113
	v_exp_f32_e32 v114, v114
	v_exp_f32_e32 v115, v115
	v_mfma_f32_32x32x16_bf16 v[16:31], v[162:165], v[180:183], v[16:31]
	v_mfma_f32_32x32x16_bf16 v[96:111], v[48:51], v[150:153], v[64:79]
	v_exp_f32_e32 v116, v116
	v_exp_f32_e32 v117, v117
	v_exp_f32_e32 v118, v118
	v_exp_f32_e32 v119, v119
	v_mfma_f32_32x32x16_bf16 v[96:111], v[52:55], v[154:157], v[96:111]
	v_cvt_pk_bf16_f32 v162, v112, v113
	v_cvt_pk_bf16_f32 v163, v114, v115
	v_cvt_pk_bf16_f32 v164, v116, v117
	v_cvt_pk_bf16_f32 v165, v118, v119
	v_pk_add_f32 v[128:129], v[128:129], v[112:113]
	v_pk_add_f32 v[128:129], v[128:129], v[114:115]
	v_pk_add_f32 v[128:129], v[128:129], v[116:117]
	v_pk_add_f32 v[128:129], v[128:129], v[118:119]
	s_waitcnt lgkmcnt(4)
	v_mfma_f32_32x32x16_bf16 v[0:15], v[162:165], v[184:187], v[0:15]
	v_exp_f32_e32 v120, v120
	v_exp_f32_e32 v121, v121
	v_exp_f32_e32 v122, v122
	v_exp_f32_e32 v123, v123
	v_mfma_f32_32x32x16_bf16 v[16:31], v[162:165], v[188:191], v[16:31]
	v_exp_f32_e32 v124, v124
	v_exp_f32_e32 v125, v125
	v_exp_f32_e32 v126, v126
	v_exp_f32_e32 v127, v127
	v_cvt_pk_bf16_f32 v162, v120, v121
	v_cvt_pk_bf16_f32 v163, v122, v123
	v_cvt_pk_bf16_f32 v164, v124, v125
	v_cvt_pk_bf16_f32 v165, v126, v127
	v_pk_add_f32 v[128:129], v[128:129], v[120:121]
	v_pk_add_f32 v[128:129], v[128:129], v[122:123]
	v_pk_add_f32 v[128:129], v[128:129], v[124:125]
	v_pk_add_f32 v[128:129], v[128:129], v[126:127]
	v_mfma_f32_32x32x16_bf16 v[112:127], v[56:59], v[150:153], v[64:79]
	v_mfma_f32_32x32x16_bf16 v[112:127], v[60:63], v[154:157], v[112:127]
	s_waitcnt lgkmcnt(0)
	v_mfma_f32_32x32x16_bf16 v[0:15], v[162:165], v[192:195], v[0:15]
	v_mfma_f32_32x32x16_bf16 v[16:31], v[162:165], v[196:199], v[16:31]
	v_exp_f32_e32 v96, v96
	v_exp_f32_e32 v97, v97
	v_exp_f32_e32 v98, v98
	v_exp_f32_e32 v99, v99
	v_exp_f32_e32 v100, v100
	v_exp_f32_e32 v101, v101
	v_exp_f32_e32 v102, v102
	v_exp_f32_e32 v103, v103
	v_cvt_pk_bf16_f32 v162, v96, v97
	v_cvt_pk_bf16_f32 v163, v98, v99
	v_cvt_pk_bf16_f32 v164, v100, v101
	v_cvt_pk_bf16_f32 v165, v102, v103
	v_pk_add_f32 v[130:131], v[130:131], v[96:97]
	v_pk_add_f32 v[130:131], v[130:131], v[98:99]
	v_pk_add_f32 v[130:131], v[130:131], v[100:101]
	v_pk_add_f32 v[130:131], v[130:131], v[102:103]
	v_mfma_f32_32x32x16_bf16 v[80:95], v[162:165], v[168:171], v[80:95]
	v_exp_f32_e32 v104, v104
	v_exp_f32_e32 v105, v105
	v_exp_f32_e32 v106, v106
	v_exp_f32_e32 v107, v107
	v_mfma_f32_32x32x16_bf16 v[200:215], v[162:165], v[172:175], v[200:215]
	v_exp_f32_e32 v108, v108
	v_exp_f32_e32 v109, v109
	v_exp_f32_e32 v110, v110
	v_exp_f32_e32 v111, v111
	v_cvt_pk_bf16_f32 v162, v104, v105
	v_cvt_pk_bf16_f32 v163, v106, v107
	v_cvt_pk_bf16_f32 v164, v108, v109
	v_cvt_pk_bf16_f32 v165, v110, v111
	v_pk_add_f32 v[130:131], v[130:131], v[104:105]
	v_pk_add_f32 v[130:131], v[130:131], v[106:107]
	v_pk_add_f32 v[130:131], v[130:131], v[108:109]
	v_pk_add_f32 v[130:131], v[130:131], v[110:111]
	v_mfma_f32_32x32x16_bf16 v[80:95], v[162:165], v[176:179], v[80:95]
	v_exp_f32_e32 v112, v112
	v_exp_f32_e32 v113, v113
	v_exp_f32_e32 v114, v114
	v_exp_f32_e32 v115, v115
	v_mfma_f32_32x32x16_bf16 v[200:215], v[162:165], v[180:183], v[200:215]
	v_exp_f32_e32 v116, v116
	v_exp_f32_e32 v117, v117
	v_exp_f32_e32 v118, v118
	v_exp_f32_e32 v119, v119
	v_cvt_pk_bf16_f32 v162, v112, v113
	v_cvt_pk_bf16_f32 v163, v114, v115
	v_cvt_pk_bf16_f32 v164, v116, v117
	v_cvt_pk_bf16_f32 v165, v118, v119
	v_pk_add_f32 v[130:131], v[130:131], v[112:113]
	v_pk_add_f32 v[130:131], v[130:131], v[114:115]
	v_pk_add_f32 v[130:131], v[130:131], v[116:117]
	v_pk_add_f32 v[130:131], v[130:131], v[118:119]
	v_mfma_f32_32x32x16_bf16 v[80:95], v[162:165], v[184:187], v[80:95]
	v_exp_f32_e32 v120, v120
	v_exp_f32_e32 v121, v121
	v_exp_f32_e32 v122, v122
	v_exp_f32_e32 v123, v123
	v_mfma_f32_32x32x16_bf16 v[200:215], v[162:165], v[188:191], v[200:215]
	v_exp_f32_e32 v124, v124
	v_exp_f32_e32 v125, v125
	v_exp_f32_e32 v126, v126
	v_exp_f32_e32 v127, v127
	v_cvt_pk_bf16_f32 v162, v120, v121
	v_cvt_pk_bf16_f32 v163, v122, v123
	v_cvt_pk_bf16_f32 v164, v124, v125
	v_cvt_pk_bf16_f32 v165, v126, v127
	v_pk_add_f32 v[130:131], v[130:131], v[120:121]
	v_pk_add_f32 v[130:131], v[130:131], v[122:123]
	v_pk_add_f32 v[130:131], v[130:131], v[124:125]
	v_pk_add_f32 v[130:131], v[130:131], v[126:127]
	s_cmp_eq_u32 s33, 21
	s_cbranch_scc1 .Lat_w0F5
	s_waitcnt vmcnt(4)
	s_branch .Lat_wdF5

; #define LAS __attribute__((address_space(3)))
; __device__ __forceinline__ int crow(int r, int hi) { return (r & 3) + 8 * (r >> 2) + 4 * hi; }
; #define AT_LOAD(K0, K1, V0, V1, T) do { const size_t e_ = (size_t)(128 * (T) + sr) * 64 + sc; \
;         K0 = *(const bf16x8*)(kcp + e_); V0 = *(const bf16x8*)(vcp + e_); K1 = *(const bf16x8*)(kcp + e_ + 64 * 64); V1 = *(const bf16x8*)(vcp + e_ + 64 * 64); } while (0)
; #define AT_STORE(K0, K1, V0, V1, BUF) do { *(LAS bf16x8*)(lds + AT_K + (BUF) * AT_KB + kst0) = K0; *(LAS bf16x8*)(lds + AT_K + (BUF) * AT_KB + kst1) = K1; \
;         *(LAS bf16x8*)(lds + AT_V + (BUF) * AT_VB + vst0) = V0; *(LAS bf16x8*)(lds + AT_V + (BUF) * AT_VB + vst1) = V1; } while (0)
; template <int VAR>
; __device__ __forceinline__ void attn_unit(const Args& a, int l, int b, int h, int qrow0  , bool ctxu, const bf16* Z, bf16* Y, LAS unsigned char* lds) {
;     ...
;     for (int t = 0; t < NT; t += 2) {
;         __syncthreads();
;         if (t + 2 < NT) AT_LOAD(ka0, ka1, va0, va1, t + 2);
;         attn_tile(Kb0, vb0, q0, q1, negm, m, o0, o1, lacc, t == 0, wsf, r32, hi);
;         AT_STORE(kb0, kb1, vb0_, vb1_, 1);
;         __syncthreads();
;         if (t + 3 < NT) AT_LOAD(kb0, kb1, vb0_, vb1_, t + 3);
;         attn_tile(Kb0 + AT_KB, vb0 + AT_VB, q0, q1, negm, m, o0, o1, lacc, false, wsf, r32, hi);
;         if (t + 2 < NT) AT_STORE(ka0, ka1, va0, va1, 0);
;     }
;     ...
;     float lam, omli;
;     { float s1 = 0.f, s2 = 0.f;
;       for (int i = 0; i < 32; ++i) { s1 += a.lam_q1[l * 32 + i] * a.lam_k1[l * 32 + i]; s2 += a.lam_q2[l * 32 + i] * a.lam_k2[l * 32 + i]; }
;       const float li = 0.8f - 0.6f * expf(-0.3f * (float)l); lam = expf(s1) - expf(s2) + li; omli = 1.f - li; }
;     LAS float* stg = (LAS float*)(lds + AT_ST) + wq * 2048;
;     if (comp == 1) {
; #pragma unroll
;         for (int r = 0; r < 16; ++r) { const int qr = crow(r, hi); const float il = lam * __builtin_amdgcn_rcpf(lacc[r]); stg[qr * 64 + r32] = o0[r] * il; stg[qr * 64 + 32 + r32] = o1[r] * il; }
;     }
;     __syncthreads();
;     if (comp == 0) {
; #pragma unroll
;         for (int r = 0; r < 16; ++r) { const int qr = crow(r, hi); const float il = __builtin_amdgcn_rcpf(lacc[r]); o0[r] = o0[r] * il - stg[qr * 64 + r32]; o1[r] = o1[r] * il - stg[qr * 64 + 32 + r32]; }
.Lat_ndF5:
	ds_read_b128 v[48:51], v144 offset:0
	ds_read_b128 v[52:55], v145 offset:0
	ds_read_b128 v[56:59], v144 offset:4096
	ds_read_b128 v[60:63], v145 offset:4096
	v_mfma_f32_32x32x16_bf16 v[80:95], v[162:165], v[192:195], v[80:95]
	v_mfma_f32_32x32x16_bf16 v[200:215], v[162:165], v[196:199], v[200:215]
	s_add_u32 s33, s33, 1
	s_cmp_lt_u32 s33, 22
	s_cbranch_scc1 .Lat_floop
	v_add_f32_e32 v132, v128, v129
	v_mov_b32_e32 v133, v132
	s_nop 1
	v_permlane32_swap_b32_e32 v132, v133
	v_add_f32_e32 v135, v132, v133
	v_add_f32_e32 v132, v130, v131
	v_mov_b32_e32 v133, v132
	s_nop 1
	v_permlane32_swap_b32_e32 v132, v133
	v_add_f32_e32 v130, v132, v133
	s_nop 7
	s_nop 7
	v_add_f32_e32 v132, v135, v130
	v_mov_b32_e32 v133, 0
	v_add_f32_e64 v132, v132, |v0|
	v_add_f32_e64 v133, v133, |v1|
	v_add_f32_e64 v132, v132, |v2|
	v_add_f32_e64 v133, v133, |v3|
	v_add_f32_e64 v132, v132, |v4|
	v_add_f32_e64 v133, v133, |v5|
	v_add_f32_e64 v132, v132, |v6|
	v_add_f32_e64 v133, v133, |v7|
	v_add_f32_e64 v132, v132, |v8|
	v_add_f32_e64 v133, v133, |v9|
	v_add_f32_e64 v132, v132, |v10|
	v_add_f32_e64 v133, v133, |v11|
	v_add_f32_e64 v132, v132, |v12|
	v_add_f32_e64 v133, v133, |v13|
	v_add_f32_e64 v132, v132, |v14|
	v_add_f32_e64 v133, v133, |v15|
	v_add_f32_e64 v132, v132, |v16|
	v_add_f32_e64 v133, v133, |v17|
	v_add_f32_e64 v132, v132, |v18|
	v_add_f32_e64 v133, v133, |v19|
	v_add_f32_e64 v132, v132, |v20|
	v_add_f32_e64 v133, v133, |v21|
	v_add_f32_e64 v132, v132, |v22|
	v_add_f32_e64 v133, v133, |v23|
	v_add_f32_e64 v132, v132, |v24|
	v_add_f32_e64 v133, v133, |v25|
	v_add_f32_e64 v132, v132, |v26|
	v_add_f32_e64 v133, v133, |v27|
	v_add_f32_e64 v132, v132, |v28|
	v_add_f32_e64 v133, v133, |v29|
	v_add_f32_e64 v132, v132, |v30|
	v_add_f32_e64 v133, v133, |v31|
	v_add_f32_e64 v132, v132, |v80|
	v_add_f32_e64 v133, v133, |v81|
	v_add_f32_e64 v132, v132, |v82|
	v_add_f32_e64 v133, v133, |v83|
	v_add_f32_e64 v132, v132, |v84|
	v_add_f32_e64 v133, v133, |v85|
	v_add_f32_e64 v132, v132, |v86|
	v_add_f32_e64 v133, v133, |v87|
	v_add_f32_e64 v132, v132, |v88|
	v_add_f32_e64 v133, v133, |v89|
	v_add_f32_e64 v132, v132, |v90|
	v_add_f32_e64 v133, v133, |v91|
	v_add_f32_e64 v132, v132, |v92|
	v_add_f32_e64 v133, v133, |v93|
	v_add_f32_e64 v132, v132, |v94|
	v_add_f32_e64 v133, v133, |v95|
	v_add_f32_e64 v132, v132, |v200|
	v_add_f32_e64 v133, v133, |v201|
	v_add_f32_e64 v132, v132, |v202|
	v_add_f32_e64 v133, v133, |v203|
	v_add_f32_e64 v132, v132, |v204|
	v_add_f32_e64 v133, v133, |v205|
	v_add_f32_e64 v132, v132, |v206|
	v_add_f32_e64 v133, v133, |v207|
	v_add_f32_e64 v132, v132, |v208|
	v_add_f32_e64 v133, v133, |v209|
	v_add_f32_e64 v132, v132, |v210|
	v_add_f32_e64 v133, v133, |v211|
	v_add_f32_e64 v132, v132, |v212|
	v_add_f32_e64 v133, v133, |v213|
	v_add_f32_e64 v132, v132, |v214|
	v_add_f32_e64 v133, v133, |v215|
	v_add_f32_e32 v132, v132, v133
	v_mov_b32_e32 v133, 0x76800000
	v_cmp_nlt_f32_e32 vcc, v132, v133
	s_cmp_lg_u64 vcc, 0
	s_cselect_b32 s50, 1, 0
	v_mov_b32_e32 v134, 0x19880
	v_mov_b32_e32 v133, s50
	ds_or_b32 v134, v133
	s_waitcnt lgkmcnt(0)
	s_barrier
	ds_read_b32 v133, v134
	s_waitcnt lgkmcnt(0)
	v_readfirstlane_b32 s50, v133
	s_cmp_lg_u32 s50, 0
	s_cbranch_scc1 .Lat_safe_entry
	s_nop 7
	s_waitcnt lgkmcnt(0)
	ds_write_b32 v148, v135
	s_waitcnt lgkmcnt(0)
	ds_read_b128 v[32:35], v147 offset:0
	ds_read_b128 v[36:39], v147 offset:32
	ds_read_b128 v[40:43], v147 offset:64
	ds_read_b128 v[44:47], v147 offset:96
	s_waitcnt lgkmcnt(0)
	s_mov_b32 s93, 0
	s_waitcnt vmcnt(0)
	s_setprio 0
	s_branch .LBB0_459

.Lat_ffirsta:
	s_nop 7
	s_nop 7
	v_max3_f32 v132, v96, v97, v98
	v_max3_f32 v133, v99, v100, v101
	v_max3_f32 v132, v132, v102, v103
	v_max3_f32 v133, v133, v104, v105
	v_max3_f32 v132, v132, v106, v107
	v_max3_f32 v133, v133, v108, v109
	v_max3_f32 v132, v132, v110, v111
	v_max3_f32 v133, v133, v112, v113
	v_max3_f32 v132, v132, v114, v115
	v_max3_f32 v133, v133, v116, v117
	v_max3_f32 v132, v132, v118, v119
	v_max3_f32 v133, v133, v120, v121
	v_max3_f32 v132, v132, v122, v123
	v_max3_f32 v133, v133, v124, v125
	v_max3_f32 v132, v132, v126, v127
	v_max_f32_e32 v132, v132, v133
	v_mov_b32_e32 v133, v132
	s_nop 1
	v_permlane32_swap_b32_e32 v132, v133
	v_max_f32_e32 v132, v132, v133
	v_mov_b32_e32 v234, v132
	v_sub_f32_e32 v96, v96, v132
	v_sub_f32_e32 v97, v97, v132
	v_sub_f32_e32 v98, v98, v132
	v_sub_f32_e32 v99, v99, v132
	v_sub_f32_e32 v100, v100, v132
	v_sub_f32_e32 v101, v101, v132
	v_sub_f32_e32 v102, v102, v132
	v_sub_f32_e32 v103, v103, v132
	v_sub_f32_e32 v104, v104, v132
	v_sub_f32_e32 v105, v105, v132
	v_sub_f32_e32 v106, v106, v132
	v_sub_f32_e32 v107, v107, v132
	v_sub_f32_e32 v108, v108, v132
	v_sub_f32_e32 v109, v109, v132
	v_sub_f32_e32 v110, v110, v132
	v_sub_f32_e32 v111, v111, v132
	v_sub_f32_e32 v112, v112, v132
	v_sub_f32_e32 v113, v113, v132
	v_sub_f32_e32 v114, v114, v132
	v_sub_f32_e32 v115, v115, v132
	v_sub_f32_e32 v116, v116, v132
	v_sub_f32_e32 v117, v117, v132
	v_sub_f32_e32 v118, v118, v132
	v_sub_f32_e32 v119, v119, v132
	v_sub_f32_e32 v120, v120, v132
	v_sub_f32_e32 v121, v121, v132
	v_sub_f32_e32 v122, v122, v132
	v_sub_f32_e32 v123, v123, v132
	v_sub_f32_e32 v124, v124, v132
	v_sub_f32_e32 v125, v125, v132
	v_sub_f32_e32 v126, v126, v132
	v_sub_f32_e32 v127, v127, v132
	v_xor_b32_e32 v32, 0x80000000, v234
	v_mov_b32_e32 v33, v32
	v_mov_b32_e32 v34, v32
	v_mov_b32_e32 v35, v32
	v_mov_b32_e32 v36, v32
	v_mov_b32_e32 v37, v32
	v_mov_b32_e32 v38, v32
	v_mov_b32_e32 v39, v32
	v_mov_b32_e32 v40, v32
	v_mov_b32_e32 v41, v32
	v_mov_b32_e32 v42, v32
	v_mov_b32_e32 v43, v32
	v_mov_b32_e32 v44, v32
	v_mov_b32_e32 v45, v32
	v_mov_b32_e32 v46, v32
	v_mov_b32_e32 v47, v32
	s_mov_b32 s94, 0
	s_branch .Lat_fbacka
.Lat_ffirstb:
	s_nop 7
	s_nop 7
	v_max3_f32 v132, v96, v97, v98
	v_max3_f32 v133, v99, v100, v101
	v_max3_f32 v132, v132, v102, v103
	v_max3_f32 v133, v133, v104, v105
	v_max3_f32 v132, v132, v106, v107
	v_max3_f32 v133, v133, v108, v109
	v_max3_f32 v132, v132, v110, v111
	v_max3_f32 v133, v133, v112, v113
	v_max3_f32 v132, v132, v114, v115
	v_max3_f32 v133, v133, v116, v117
	v_max3_f32 v132, v132, v118, v119
	v_max3_f32 v133, v133, v120, v121
	v_max3_f32 v132, v132, v122, v123
	v_max3_f32 v133, v133, v124, v125
	v_max3_f32 v132, v132, v126, v127
	v_max_f32_e32 v132, v132, v133
	v_mov_b32_e32 v133, v132
	s_nop 1
	v_permlane32_swap_b32_e32 v132, v133
	v_max_f32_e32 v132, v132, v133
	v_mov_b32_e32 v149, v132
	v_sub_f32_e32 v96, v96, v132
	v_sub_f32_e32 v97, v97, v132
	v_sub_f32_e32 v98, v98, v132
	v_sub_f32_e32 v99, v99, v132
	v_sub_f32_e32 v100, v100, v132
	v_sub_f32_e32 v101, v101, v132
	v_sub_f32_e32 v102, v102, v132
	v_sub_f32_e32 v103, v103, v132
	v_sub_f32_e32 v104, v104, v132
	v_sub_f32_e32 v105, v105, v132
	v_sub_f32_e32 v106, v106, v132
	v_sub_f32_e32 v107, v107, v132
	v_sub_f32_e32 v108, v108, v132
	v_sub_f32_e32 v109, v109, v132
	v_sub_f32_e32 v110, v110, v132
	v_sub_f32_e32 v111, v111, v132
	v_sub_f32_e32 v112, v112, v132
	v_sub_f32_e32 v113, v113, v132
	v_sub_f32_e32 v114, v114, v132
	v_sub_f32_e32 v115, v115, v132
	v_sub_f32_e32 v116, v116, v132
	v_sub_f32_e32 v117, v117, v132
	v_sub_f32_e32 v118, v118, v132
	v_sub_f32_e32 v119, v119, v132
	v_sub_f32_e32 v120, v120, v132
	v_sub_f32_e32 v121, v121, v132
	v_sub_f32_e32 v122, v122, v132
	v_sub_f32_e32 v123, v123, v132
	v_sub_f32_e32 v124, v124, v132
	v_sub_f32_e32 v125, v125, v132
	v_sub_f32_e32 v126, v126, v132
	v_sub_f32_e32 v127, v127, v132
	v_xor_b32_e32 v64, 0x80000000, v149
	v_mov_b32_e32 v65, v64
	v_mov_b32_e32 v66, v64
	v_mov_b32_e32 v67, v64
	v_mov_b32_e32 v68, v64
	v_mov_b32_e32 v69, v64
	v_mov_b32_e32 v70, v64
	v_mov_b32_e32 v71, v64
	v_mov_b32_e32 v72, v64
	v_mov_b32_e32 v73, v64
	v_mov_b32_e32 v74, v64
	v_mov_b32_e32 v75, v64
	v_mov_b32_e32 v76, v64
	v_mov_b32_e32 v77, v64
	v_mov_b32_e32 v78, v64
	v_mov_b32_e32 v79, v64
	s_mov_b32 s95, 0
	s_branch .Lat_fbackb
; #define LAS __attribute__((address_space(3)))
; __device__ __forceinline__ int v_st_nat(int k, int c) { return ((k >> 3) * 2 + (c >> 5)) * 512 + ((k & 7) * 32 + (c & 31)) * 2; }
; __device__ __forceinline__ int v_rd_base(int lane) { return ((lane & 3) << 3) | (((lane >> 2) & 3) << 6) | (((lane >> 4) & 1) << 5) | (((lane >> 5) & 1) << 8); }
; #define AT_LOAD(K0, K1, V0, V1, T) do { const size_t e_ = (size_t)(128 * (T) + sr) * 64 + sc; \
;         K0 = *(const bf16x8*)(kcp + e_); V0 = *(const bf16x8*)(vcp + e_); K1 = *(const bf16x8*)(kcp + e_ + 64 * 64); V1 = *(const bf16x8*)(vcp + e_ + 64 * 64); } while (0)
; #define AT_STORE(K0, K1, V0, V1, BUF) do { *(LAS bf16x8*)(lds + AT_K + (BUF) * AT_KB + kst0) = K0; *(LAS bf16x8*)(lds + AT_K + (BUF) * AT_KB + kst1) = K1; \
;         *(LAS bf16x8*)(lds + AT_V + (BUF) * AT_VB + vst0) = V0; *(LAS bf16x8*)(lds + AT_V + (BUF) * AT_VB + vst1) = V1; } while (0)
; template <int VAR>
; __device__ __forceinline__ void attn_unit(const Args& a, int l, int b, int h, int qrow0  , bool ctxu, const bf16* Z, bf16* Y, LAS unsigned char* lds) {
;     ...
;     const int sr = tid >> 3, sc = (tid & 7) * 8;
;     const int kst0 = sr * 144 + sc * 2, kst1 = kst0 + 64 * 144, vst0 = v_st_nat(sr, sc), vst1 = v_st_nat(sr + 64, sc);
;     const int vb0 = (int)(unsigned)(uintptr_t)(lds + AT_V) + v_rd_base(lane);
;     LAS float* wsf = (LAS float*)(lds + AT_WS) + wave * 64;
;     f32x16 negm = f32x16{}, o0 = f32x16{}, o1 = f32x16{}, lacc = f32x16{};
;     float m = 0.f;
;     bf16x8 ka0, ka1, va0, va1, kb0, kb1, vb0_, vb1_;
;     ...
;     AT_LOAD(ka0, ka1, va0, va1, 0); AT_LOAD(kb0, kb1, vb0_, vb1_, 1); AT_STORE(ka0, ka1, va0, va1, 0);
;     const LAS unsigned char* Kb0 = lds + AT_K + comp * 64;
.Lat_safe_entry:
	s_barrier
	v_mov_b32_e32 v0, 0
	v_mov_b32_e32 v1, 0
	v_mov_b32_e32 v2, 0
	v_mov_b32_e32 v3, 0
	v_mov_b32_e32 v4, 0
	v_mov_b32_e32 v5, 0
	v_mov_b32_e32 v6, 0
	v_mov_b32_e32 v7, 0
	v_mov_b32_e32 v8, 0
	v_mov_b32_e32 v9, 0
	v_mov_b32_e32 v10, 0
	v_mov_b32_e32 v11, 0
	v_mov_b32_e32 v12, 0
	v_mov_b32_e32 v13, 0
	v_mov_b32_e32 v14, 0
	v_mov_b32_e32 v15, 0
	v_mov_b32_e32 v16, 0
	v_mov_b32_e32 v17, 0
	v_mov_b32_e32 v18, 0
	v_mov_b32_e32 v19, 0
	v_mov_b32_e32 v20, 0
	v_mov_b32_e32 v21, 0
	v_mov_b32_e32 v22, 0
	v_mov_b32_e32 v23, 0
	v_mov_b32_e32 v24, 0
	v_mov_b32_e32 v25, 0
	v_mov_b32_e32 v26, 0
	v_mov_b32_e32 v27, 0
	v_mov_b32_e32 v28, 0
	v_mov_b32_e32 v29, 0
	v_mov_b32_e32 v30, 0
	v_mov_b32_e32 v31, 0
	v_mov_b32_e32 v32, 0
	v_mov_b32_e32 v33, 0
	v_mov_b32_e32 v34, 0
	v_mov_b32_e32 v35, 0
	v_mov_b32_e32 v36, 0
	v_mov_b32_e32 v37, 0
	v_mov_b32_e32 v38, 0
	v_mov_b32_e32 v39, 0
	v_mov_b32_e32 v40, 0
	v_mov_b32_e32 v41, 0
	v_mov_b32_e32 v42, 0
	v_mov_b32_e32 v43, 0
	v_mov_b32_e32 v44, 0
	v_mov_b32_e32 v45, 0
	v_mov_b32_e32 v46, 0
	v_mov_b32_e32 v47, 0
	v_mov_b32_e32 v64, 0
	v_mov_b32_e32 v65, 0
	v_mov_b32_e32 v66, 0
	v_mov_b32_e32 v67, 0
	v_mov_b32_e32 v68, 0
	v_mov_b32_e32 v69, 0
	v_mov_b32_e32 v70, 0
	v_mov_b32_e32 v71, 0
	v_mov_b32_e32 v72, 0
	v_mov_b32_e32 v73, 0
	v_mov_b32_e32 v74, 0
	v_mov_b32_e32 v75, 0
	v_mov_b32_e32 v76, 0
	v_mov_b32_e32 v77, 0
	v_mov_b32_e32 v78, 0
	v_mov_b32_e32 v79, 0
	v_mov_b32_e32 v234, 0
	v_mov_b32_e32 v79, 0
	v_readfirstlane_b32 s36, v230
	v_readfirstlane_b32 s37, v231
	s_mov_b32 s94, 1
	s_mov_b32 s95, 1
	s_mov_b32 s33, 0
	s_lshr_b32 s50, s29, 6
	s_lshl_b32 s51, s50, 10
	s_lshl_b32 s93, s50, 8
	s_lshl_b32 s50, s50, 3
	v_lshrrev_b32_e32 v132, 3, v227
	v_add_u32_e32 v132, s50, v132
	v_bfe_u32 v133, v132, 1, 3
	v_and_b32_e32 v134, 7, v227
	v_xor_b32_e32 v134, v134, v133
	v_lshlrev_b32_e32 v132, 7, v132
	v_lshl_or_b32 v158, v134, 4, v132
	v_add_u32_e32 v159, 0x2000, v158
	v_bfe_u32 v132, v227, 2, 3
	v_add_u32_e32 v132, s50, v132
	v_lshrrev_b32_e32 v133, 5, v227
	v_and_b32_e32 v134, 3, v227
	v_lshlrev_b32_e32 v133, 6, v133
	v_lshl_or_b32 v133, v134, 4, v133
	v_lshl_or_b32 v160, v132, 7, v133
	v_add_u32_e32 v161, 0x2000, v160
	s_lshl_b32 s50, s8, 2
	v_add_u32_e32 v132, s50, v248
	v_bfe_u32 v133, v247, 1, 3
	v_xor_b32_e32 v132, v132, v133
	v_lshlrev_b32_e32 v133, 7, v247
	v_lshl_or_b32 v144, v132, 4, v133
	v_xor_b32_e32 v145, 32, v144
	v_add_u32_e32 v146, 0x3000, v249
	s_add_u32 s93, s93, 0x19800
	v_lshlrev_b32_e32 v132, 2, v247
	v_add_u32_e32 v148, s93, v132
	v_lshlrev_b32_e32 v132, 4, v248
	v_add_u32_e32 v147, s93, v132
	v_mov_b32_e32 v132, 0x19880
	v_mov_b32_e32 v133, 0
	ds_write_b32 v132, v133
	v_mov_b32_e32 v80, 0
	v_mov_b32_e32 v200, 0
	v_mov_b32_e32 v81, 0
	v_mov_b32_e32 v201, 0
	v_mov_b32_e32 v82, 0
	v_mov_b32_e32 v202, 0
	v_mov_b32_e32 v83, 0
	v_mov_b32_e32 v203, 0
	v_mov_b32_e32 v84, 0
	v_mov_b32_e32 v204, 0
	v_mov_b32_e32 v85, 0
	v_mov_b32_e32 v205, 0
	v_mov_b32_e32 v86, 0
	v_mov_b32_e32 v206, 0
	v_mov_b32_e32 v87, 0
	v_mov_b32_e32 v207, 0
	v_mov_b32_e32 v88, 0
	v_mov_b32_e32 v208, 0
	v_mov_b32_e32 v89, 0
	v_mov_b32_e32 v209, 0
	v_mov_b32_e32 v90, 0
	v_mov_b32_e32 v210, 0
	v_mov_b32_e32 v91, 0
	v_mov_b32_e32 v211, 0
	v_mov_b32_e32 v92, 0
	v_mov_b32_e32 v212, 0
	v_mov_b32_e32 v93, 0
	v_mov_b32_e32 v213, 0
	v_mov_b32_e32 v94, 0
	v_mov_b32_e32 v214, 0
	v_mov_b32_e32 v95, 0
	v_mov_b32_e32 v215, 0
	v_mov_b32_e32 v128, 0
	v_mov_b32_e32 v129, 0
	v_mov_b32_e32 v130, 0
	v_mov_b32_e32 v131, 0
	v_mov_b32_e32 v149, 0
	s_sub_u32 s36, s36, s51
	s_subb_u32 s37, s37, 0
	s_add_u32 s48, s36, 0x1d200000
	s_addc_u32 s49, s37, 0
	s_add_u32 s36, s36, 0x1c000000
	s_addc_u32 s37, s37, 0
	s_cmp_eq_u32 s8, 0
	s_cbranch_scc0 .Lat_noprioS
	s_setprio 1

.Lat_ndg5:
	ds_read_b128 v[48:51], v144 offset:0
	ds_read_b128 v[52:55], v145 offset:0
	ds_read_b128 v[56:59], v144 offset:4096
	ds_read_b128 v[60:63], v145 offset:4096
	v_mfma_f32_32x32x16_bf16 v[80:95], v[162:165], v[192:195], v[80:95]
	v_mfma_f32_32x32x16_bf16 v[200:215], v[162:165], v[196:199], v[200:215]
	s_add_u32 s33, s33, 1
	s_cmp_lt_u32 s33, 22
	s_cbranch_scc1 .Lat_loop
	v_add_f32_e32 v132, v128, v129
	v_mov_b32_e32 v133, v132
	s_nop 1
	v_permlane32_swap_b32_e32 v132, v133
	v_add_f32_e32 v135, v132, v133
	v_add_f32_e32 v132, v130, v131
	v_mov_b32_e32 v133, v132
	s_nop 1
	v_permlane32_swap_b32_e32 v132, v133
	v_add_f32_e32 v130, v132, v133
	s_nop 7
	s_waitcnt lgkmcnt(0)
	ds_write_b32 v148, v135
	s_waitcnt lgkmcnt(0)
	ds_read_b128 v[32:35], v147 offset:0
	ds_read_b128 v[36:39], v147 offset:32
	ds_read_b128 v[40:43], v147 offset:64
	ds_read_b128 v[44:47], v147 offset:96
	s_waitcnt lgkmcnt(0)
	s_mov_b32 s93, 0
	s_waitcnt vmcnt(0)
	s_setprio 0
	s_branch .LBB0_459
.Lat_rareg0a:
	v_mov_b32_e32 v133, v132
	s_nop 1
	v_permlane32_swap_b32_e32 v132, v133
	v_max_f32_e32 v132, v132, v133
	s_cmp_lg_u32 s94, 0
	s_cbranch_scc1 .Lat_firstSa
	v_max_f32_e32 v132, 0, v132
	v_exp_f32_e64 v133, -v132
	v_add_f32_e32 v234, v234, v132
	s_nop 0
	ds_write_b32 v148, v133
	v_mul_f32_e32 v128, v128, v133
	v_mul_f32_e32 v129, v129, v133
	v_sub_f32_e32 v96, v96, v132
	v_sub_f32_e32 v97, v97, v132
	v_sub_f32_e32 v98, v98, v132
	v_sub_f32_e32 v99, v99, v132
	v_sub_f32_e32 v100, v100, v132
	v_sub_f32_e32 v101, v101, v132
	v_sub_f32_e32 v102, v102, v132
	v_sub_f32_e32 v103, v103, v132
	v_sub_f32_e32 v104, v104, v132
	v_sub_f32_e32 v105, v105, v132
	v_sub_f32_e32 v106, v106, v132
	v_sub_f32_e32 v107, v107, v132
	v_sub_f32_e32 v108, v108, v132
	v_sub_f32_e32 v109, v109, v132
	v_sub_f32_e32 v110, v110, v132
	v_sub_f32_e32 v111, v111, v132
	v_sub_f32_e32 v112, v112, v132
	v_sub_f32_e32 v113, v113, v132
	v_sub_f32_e32 v114, v114, v132
	v_sub_f32_e32 v115, v115, v132
	v_sub_f32_e32 v116, v116, v132
	v_sub_f32_e32 v117, v117, v132
	v_sub_f32_e32 v118, v118, v132
	v_sub_f32_e32 v119, v119, v132
	v_sub_f32_e32 v120, v120, v132
	v_sub_f32_e32 v121, v121, v132
	v_sub_f32_e32 v122, v122, v132
	v_sub_f32_e32 v123, v123, v132
	v_sub_f32_e32 v124, v124, v132
	v_sub_f32_e32 v125, v125, v132
	v_sub_f32_e32 v126, v126, v132
	v_sub_f32_e32 v127, v127, v132
	v_xor_b32_e32 v32, 0x80000000, v234
	v_mov_b32_e32 v33, v32
	v_mov_b32_e32 v34, v32
	v_mov_b32_e32 v35, v32
	v_mov_b32_e32 v36, v32
	v_mov_b32_e32 v37, v32
	v_mov_b32_e32 v38, v32
	v_mov_b32_e32 v39, v32
	v_mov_b32_e32 v40, v32
	v_mov_b32_e32 v41, v32
	v_mov_b32_e32 v42, v32
	v_mov_b32_e32 v43, v32
	v_mov_b32_e32 v44, v32
	v_mov_b32_e32 v45, v32
	v_mov_b32_e32 v46, v32
	v_mov_b32_e32 v47, v32
	s_waitcnt lgkmcnt(0)
	ds_read_b128 v[162:165], v147 offset:0
	s_waitcnt lgkmcnt(0)
	v_mul_f32_e32 v0, v0, v162
	v_mul_f32_e32 v16, v16, v162
	v_mul_f32_e32 v1, v1, v163
	v_mul_f32_e32 v17, v17, v163
	v_mul_f32_e32 v2, v2, v164
	v_mul_f32_e32 v18, v18, v164
	v_mul_f32_e32 v3, v3, v165
	v_mul_f32_e32 v19, v19, v165
	ds_read_b128 v[162:165], v147 offset:32
	s_waitcnt lgkmcnt(0)
	v_mul_f32_e32 v4, v4, v162
	v_mul_f32_e32 v20, v20, v162
	v_mul_f32_e32 v5, v5, v163
	v_mul_f32_e32 v21, v21, v163
	v_mul_f32_e32 v6, v6, v164
	v_mul_f32_e32 v22, v22, v164
	v_mul_f32_e32 v7, v7, v165
	v_mul_f32_e32 v23, v23, v165
	ds_read_b128 v[162:165], v147 offset:64
	s_waitcnt lgkmcnt(0)
	v_mul_f32_e32 v8, v8, v162
	v_mul_f32_e32 v24, v24, v162
	v_mul_f32_e32 v9, v9, v163
	v_mul_f32_e32 v25, v25, v163
	v_mul_f32_e32 v10, v10, v164
	v_mul_f32_e32 v26, v26, v164
	v_mul_f32_e32 v11, v11, v165
	v_mul_f32_e32 v27, v27, v165
	ds_read_b128 v[162:165], v147 offset:96
	s_waitcnt lgkmcnt(0)
	v_mul_f32_e32 v12, v12, v162
	v_mul_f32_e32 v28, v28, v162
	v_mul_f32_e32 v13, v13, v163
	v_mul_f32_e32 v29, v29, v163
	v_mul_f32_e32 v14, v14, v164
	v_mul_f32_e32 v30, v30, v164
	v_mul_f32_e32 v15, v15, v165
	v_mul_f32_e32 v31, v31, v165
	s_branch .Lat_backg0a
